# v025 + s_setprio 1/0 around the eight MFMA clusters (QK, PV) of the neighbourhood-attention phase
# baseline (speedup 1.0000x reference)
; #define VM0() asm volatile("s_waitcnt vmcnt(0)" ::: "memory")
; template <bool QL>
; __device__ __forceinline__ void qkt(f32x16& p0, f32x16& p1, const bf16* Ks, const bf16x8* qr, const char* ql, int r32, int hi) {
;   p0 = f32x16{}; p1 = f32x16{};
;   for (int d0 = 0; d0 < 8; ++d0) { int cb = (d0 * 16 + hi * 8) * 2;
;     bf16x8 b0 = *reinterpret_cast<const bf16x8*>((const char*)Ks + KSWZ(r32, cb));
;     bf16x8 b1 = *reinterpret_cast<const bf16x8*>((const char*)Ks + KSWZ(32 + r32, cb));
; template <bool NA, int ROWB>
; __device__ __forceinline__ void attn_dma(const bf16* __restrict__ Qb, const bf16* __restrict__ Kh, const bf16* __restrict__ Vh, bf16* __restrict__ Ob, int NT, char* lds, const int tid, float* __restrict__ ssb, int qrow0, int kr_lo, const float* bl) {
;   const int wid = tid >> 6, lane = tid & 63, r32 = lane & 31, hi = lane >> 5;
;   const int wid_s = __builtin_amdgcn_readfirstlane(wid);
;   char* V_lds = lds; char* K_lds = lds + 3 * SHM_V;
;   float* li_l = (float*)(lds + 3 * SHM_V + 3 * SHM_K) + wid * 64;
;   float* al_l = li_l + 32;
;   float m_reg = -1e30f, l_reg = 0; f32x16 o[4] = {}; bf16x8 qr[8];
;   const int qrow = qrow0 + (wid >> 1), qc = 32 * (wid & 1) + r32;
;   const int c0 = min(max(qc - 8, 0), 48), r0 = min(max(qrow - 4, 0), 120);
;   const bf16* Qw = Qb + (long)(wid * QBLK + r32) * LDQ + hi * 8;
; #pragma unroll
;   for (int d0 = 0; d0 < 8; ++d0) qr[d0] = *reinterpret_cast<const bf16x8*>(Qw + d0 * 16);
;   const int vb0 = (int)(uintptr_t)V_lds + v_rd_base(lane);
;   auto src_off = [&](int i, unsigned& ko, unsigned& vo) __attribute__((always_inline)) {
;     const int b = (wid * 2 + i) * 1024 + lane * 16;
;     { const int row = b >> 8, cb = (b & 255) ^ ((row & 7) << 4); ko = (unsigned)(row * ROWB + cb); }
;     { const int st = b >> 9, within = b & 511, kk = (st >> 2) * 8 + (within >> 6), c = (st & 3) * 32 + ((within & 63) >> 1);
;       const int k = (kk & ~0xC) | ((kk & 4) << 1) | ((kk & 8) >> 1); vo = (unsigned)(k * ROWB + c * 2); }
;   };
;   unsigned ksrc[2], vsrc[2];
;   if constexpr (!NA) { src_off(0, ksrc[0], vsrc[0]); src_off(1, ksrc[1], vsrc[1]); }
;     ...
;   f32x16 pA0, pA1, pB0, pB1; bf16x8 pa0, pa1, pa2, pa3; float mnA, mnB, alA, alB;
;   DMA_TILE(0, 0); DMA_TILE(1, 1); VM0(); __syncthreads();
;   qkt<false>(pA0, pA1, (const bf16*)K_lds, qr, nullptr, r32, hi); NAM(pA0, pA1, 0); PSM(pA0, pA1, mnA, alA);
.LBB0_145:
	s_or_b64 exec, exec, s[18:19]
	s_ashr_i32 s0, s25, 3
	s_waitcnt lgkmcnt(0)
	s_lshl_b32 s22, s0, 8
	s_mov_b32 s18, s22
	s_lshl_b32 s14, s0, 2
	v_writelane_b32 v254, s18, 51
	s_max_i32 s37, s14, 4
	s_add_i32 s16, s37, -4
	v_writelane_b32 v254, s19, 52
	s_mul_i32 s1, s0, 0x240000
	v_readlane_b32 s38, v254, 47
	s_mul_hi_i32 s15, s22, 0x2400
	v_readlane_b32 s39, v254, 48
	s_add_u32 s1, s38, s1
	s_addc_u32 s15, s39, s15
	s_lshl_b32 s22, s36, 8
	s_add_u32 s18, s1, s22
	s_addc_u32 s19, s15, 0
	v_lshl_add_u64 v[0:1], s[18:19], 0, v[130:131]
	v_lshl_add_u64 v[0:1], v[0:1], 0, v[112:113]
	global_load_dwordx4 v[100:103], v[0:1], off
	global_load_dwordx4 v[126:129], v[0:1], off offset:32
	global_load_dwordx4 v[122:125], v[0:1], off offset:64
	global_load_dwordx4 v[118:121], v[0:1], off offset:96
	global_load_dwordx4 v[114:117], v[0:1], off offset:128
	global_load_dwordx4 v[108:111], v[0:1], off offset:160
	global_load_dwordx4 v[104:107], v[0:1], off offset:192
	global_load_dwordx4 v[96:99], v[0:1], off offset:224
	s_mul_i32 s1, s16, 0x90000
	s_lshl_b32 s17, s16, 6
	s_mul_hi_u32 s17, s17, 0x2400
	s_add_u32 s18, s38, s1
	s_addc_u32 s19, s39, s17
	s_add_u32 s18, s18, s22
	s_addc_u32 s19, s19, 0
	v_readfirstlane_b32 s15, v168
	s_add_u32 s22, s18, 0x1000
	s_addc_u32 s23, s19, 0
	s_lshl_b32 s33, s15, 11
	v_lshl_add_u64 v[0:1], s[18:19], 0, v[132:133]
	s_add_i32 s38, s33, 0
	v_lshl_add_u64 v[0:1], v[0:1], 0, s[28:29]
	s_add_i32 m0, s38, 0xc000
	v_lshl_add_u64 v[2:3], s[18:19], 0, v[136:137]
	v_lshl_add_u64 v[4:5], s[22:23], 0, v[134:135]
	global_load_lds_dwordx4 v[0:1], off
	s_mov_b32 m0, s38
	v_lshl_add_u64 v[2:3], v[2:3], 0, s[28:29]
	global_load_lds_dwordx4 v[4:5], off
	s_add_i32 m0, s38, 0xc400
	v_lshl_add_u64 v[6:7], s[22:23], 0, v[138:139]
	global_load_lds_dwordx4 v[2:3], off
	s_add_i32 m0, s38, 0x400
	s_add_u32 s22, s18, 0x90800
	s_addc_u32 s23, s19, 0
	s_add_u32 s18, s18, 0x91000
	global_load_lds_dwordx4 v[6:7], off
	v_lshl_add_u64 v[0:1], s[22:23], 0, v[132:133]
	s_addc_u32 s19, s19, 0
	s_add_i32 m0, s38, 0x10000
	v_lshl_add_u64 v[2:3], s[22:23], 0, v[136:137]
	global_load_lds_dwordx4 v[0:1], off
	v_lshl_add_u64 v[0:1], s[18:19], 0, v[134:135]
	s_add_i32 m0, s38, 0x4000
	v_lshl_add_u64 v[4:5], s[18:19], 0, v[138:139]
	global_load_lds_dwordx4 v[0:1], off
	s_add_i32 m0, s38, 0x10400
	v_add_u32_e32 v8, 0, v173
	global_load_lds_dwordx4 v[2:3], off
	s_add_i32 m0, s38, 0x4400
	v_add_u32_e32 v36, 0, v174
	global_load_lds_dwordx4 v[4:5], off
	s_waitcnt vmcnt(0)
	s_waitcnt vmcnt(0) lgkmcnt(0)
	s_barrier
	ds_read_b128 v[0:3], v8 offset:49152
	ds_read_b128 v[32:35], v36 offset:49152
	v_add_u32_e32 v189, s14, v170
	s_waitcnt lgkmcnt(1)
	s_setprio 1
	v_mfma_f32_32x32x16_bf16 v[16:31], v[0:3], v[100:103], 0
	ds_read_b128 v[0:3], v8 offset:57344
	s_waitcnt lgkmcnt(1)
	v_mfma_f32_32x32x16_bf16 v[16:31], v[32:35], v[126:129], v[16:31]
	ds_read_b128 v[32:35], v36 offset:57344
	v_add_u32_e32 v36, 0, v175
	s_waitcnt lgkmcnt(1)
	v_mfma_f32_32x32x16_bf16 v[0:15], v[0:3], v[100:103], 0
	s_waitcnt lgkmcnt(0)
	v_mfma_f32_32x32x16_bf16 v[0:15], v[32:35], v[126:129], v[0:15]
	ds_read_b128 v[32:35], v36 offset:49152
	s_waitcnt lgkmcnt(0)
	v_mfma_f32_32x32x16_bf16 v[16:31], v[32:35], v[122:125], v[16:31]
	ds_read_b128 v[32:35], v36 offset:57344
	v_add_u32_e32 v36, 0, v176
	s_waitcnt lgkmcnt(0)
	v_mfma_f32_32x32x16_bf16 v[0:15], v[32:35], v[122:125], v[0:15]
	ds_read_b128 v[32:35], v36 offset:49152
	s_waitcnt lgkmcnt(0)
	v_mfma_f32_32x32x16_bf16 v[16:31], v[32:35], v[118:121], v[16:31]
	ds_read_b128 v[32:35], v36 offset:57344
	v_add_u32_e32 v36, 0, v177
	s_waitcnt lgkmcnt(0)
	v_mfma_f32_32x32x16_bf16 v[0:15], v[32:35], v[118:121], v[0:15]
	ds_read_b128 v[32:35], v36 offset:49152
	s_waitcnt lgkmcnt(0)
	v_mfma_f32_32x32x16_bf16 v[16:31], v[32:35], v[114:117], v[16:31]
	ds_read_b128 v[32:35], v36 offset:57344
	v_add_u32_e32 v36, 0, v178
	s_waitcnt lgkmcnt(0)
	v_mfma_f32_32x32x16_bf16 v[0:15], v[32:35], v[114:117], v[0:15]
	ds_read_b128 v[32:35], v36 offset:49152
	s_waitcnt lgkmcnt(0)
	v_mfma_f32_32x32x16_bf16 v[16:31], v[32:35], v[108:111], v[16:31]
	ds_read_b128 v[32:35], v36 offset:57344
	v_add_u32_e32 v36, 0, v179
	s_waitcnt lgkmcnt(0)
	v_mfma_f32_32x32x16_bf16 v[0:15], v[32:35], v[108:111], v[0:15]
	ds_read_b128 v[32:35], v36 offset:49152
	s_waitcnt lgkmcnt(0)
	v_mfma_f32_32x32x16_bf16 v[16:31], v[32:35], v[104:107], v[16:31]
	ds_read_b128 v[32:35], v36 offset:57344
	v_add_u32_e32 v36, 0, v180
	s_waitcnt lgkmcnt(0)
	v_mfma_f32_32x32x16_bf16 v[0:15], v[32:35], v[104:107], v[0:15]
	ds_read_b128 v[32:35], v36 offset:49152
	s_waitcnt lgkmcnt(0)
	v_mfma_f32_32x32x16_bf16 v[16:31], v[32:35], v[96:99], v[16:31]
	ds_read_b128 v[32:35], v36 offset:57344
	v_max_i32_e32 v36, 4, v189
	v_add_u32_e32 v36, -4, v36
	v_min_u32_e32 v190, 0x78, v36
	v_add_u32_e32 v191, 8, v190
	v_cmp_lt_u32_e32 vcc, s16, v190
	v_cmp_ge_u32_e64 s[18:19], s16, v191
	s_waitcnt lgkmcnt(0)
	v_mfma_f32_32x32x16_bf16 v[0:15], v[32:35], v[96:99], v[0:15]
	s_setprio 0
	s_or_b64 s[14:15], vcc, s[18:19]
	s_and_saveexec_b64 s[18:19], s[14:15]
	s_xor_b64 s[14:15], exec, s[18:19]
	s_or_saveexec_b64 s[18:19], s[14:15]
	v_mov_b32_e32 v36, 0xf149f2ca
	v_mov_b32_e32 v35, 0xf149f2ca
	v_mov_b32_e32 v34, 0xf149f2ca
	v_mov_b32_e32 v33, 0xf149f2ca
	v_mov_b32_e32 v32, 0xf149f2ca
	v_mov_b32_e32 v39, 0xf149f2ca
	v_mov_b32_e32 v38, 0xf149f2ca
	v_mov_b32_e32 v41, 0xf149f2ca
	v_mov_b32_e32 v40, 0xf149f2ca
	v_mov_b32_e32 v43, 0xf149f2ca
	v_mov_b32_e32 v42, 0xf149f2ca
	v_mov_b32_e32 v45, 0xf149f2ca
	v_mov_b32_e32 v44, 0xf149f2ca
	v_mov_b32_e32 v47, 0xf149f2ca
	v_mov_b32_e32 v46, 0xf149f2ca
	v_mov_b32_e32 v62, 0xf149f2ca
	v_mov_b32_e32 v63, 0xf149f2ca
	v_mov_b32_e32 v60, 0xf149f2ca
	v_mov_b32_e32 v61, 0xf149f2ca
	v_mov_b32_e32 v58, 0xf149f2ca
	v_mov_b32_e32 v59, 0xf149f2ca
	v_mov_b32_e32 v56, 0xf149f2ca
	v_mov_b32_e32 v57, 0xf149f2ca
	v_mov_b32_e32 v54, 0xf149f2ca
	v_mov_b32_e32 v55, 0xf149f2ca
	v_mov_b32_e32 v52, 0xf149f2ca
	v_mov_b32_e32 v53, 0xf149f2ca
	v_mov_b32_e32 v50, 0xf149f2ca
	v_mov_b32_e32 v51, 0xf149f2ca
	v_mov_b32_e32 v48, 0xf149f2ca
	v_mov_b32_e32 v49, 0xf149f2ca
	v_mov_b32_e32 v37, 0xf149f2ca
	s_xor_b64 exec, exec, s[18:19]
	s_cbranch_execz .LBB0_181
; __device__ __forceinline__ void na_mask(f32x16& p0, f32x16& p1, int kr, int r0, int qrow, int qc, int c0, int hi, const float* bl) {
;     ...
;   } else {
;     const float* brow = bl + (kr - qrow + 7) * 31 + 15 - qc + 4 * hi;
;     const int d = 4 * hi - c0;
; #pragma unroll
;     for (int r = 0; r < 16; ++r) {
;       const int kc = (r & 3) + 8 * (r >> 2);
;       const float b0 = brow[kc], b1 = brow[kc + 32];
;       p0[r] = (unsigned)(d + kc) < 16u ? p0[r] + b0 : -1e30f; p1[r] = (unsigned)(d + kc + 32) < 16u ? p1[r] + b1 : -1e30f;
;     }
;   }
	v_sub_u32_e32 v32, s16, v189
	s_movk_i32 s14, 0x7c
	v_mul_lo_u32 v32, v32, s14
	v_add_u32_e32 v33, v184, v32
	ds_read_b32 v32, v33 offset:188
	v_mov_b32_e32 v48, 0xf149f2ca
	v_mov_b32_e32 v49, 0xf149f2ca
	v_mov_b32_e32 v50, 0xf149f2ca
	v_mov_b32_e32 v51, 0xf149f2ca
	v_mov_b32_e32 v52, 0xf149f2ca
	v_mov_b32_e32 v53, 0xf149f2ca
	v_mov_b32_e32 v54, 0xf149f2ca
	v_mov_b32_e32 v55, 0xf149f2ca
	v_mov_b32_e32 v56, 0xf149f2ca
	v_mov_b32_e32 v57, 0xf149f2ca
	v_mov_b32_e32 v58, 0xf149f2ca
	v_mov_b32_e32 v59, 0xf149f2ca
	v_mov_b32_e32 v60, 0xf149f2ca
	v_mov_b32_e32 v61, 0xf149f2ca
	v_mov_b32_e32 v62, 0xf149f2ca
	v_mov_b32_e32 v63, 0xf149f2ca
	ds_read_b32 v49, v33 offset:60
	ds_read_b32 v48, v33 offset:64
	ds_read_b32 v51, v33 offset:68
	ds_read_b32 v50, v33 offset:72
	ds_read_b32 v53, v33 offset:92
	ds_read_b32 v52, v33 offset:96
	ds_read_b32 v55, v33 offset:100
	ds_read_b32 v54, v33 offset:104
	ds_read_b32 v57, v33 offset:124
	ds_read_b32 v56, v33 offset:128
	ds_read_b32 v59, v33 offset:132
	ds_read_b32 v58, v33 offset:136
	ds_read_b32 v61, v33 offset:156
	ds_read_b32 v60, v33 offset:160
	ds_read_b32 v63, v33 offset:164
	ds_read_b32 v62, v33 offset:168
	s_waitcnt lgkmcnt(0)
	v_add_f32_e32 v49, v16, v49
	v_add_f32_e32 v48, v17, v48
	v_add_f32_e32 v51, v18, v51
	v_add_f32_e32 v50, v19, v50
	v_add_f32_e32 v53, v20, v53
	v_add_f32_e32 v52, v21, v52
	v_add_f32_e32 v55, v22, v55
	v_add_f32_e32 v54, v23, v54
	v_add_f32_e32 v57, v24, v57
	v_add_f32_e32 v56, v25, v56
	v_add_f32_e32 v59, v26, v59
	v_add_f32_e32 v58, v27, v58
	v_add_f32_e32 v61, v28, v61
	v_add_f32_e32 v60, v29, v60
	v_add_f32_e32 v63, v30, v63
	v_add_f32_e32 v62, v31, v62
	ds_read_b32 v16, v33 offset:192
	ds_read_b32 v17, v33 offset:196
	ds_read_b32 v18, v33 offset:200
	ds_read_b32 v19, v33 offset:220
	ds_read_b32 v20, v33 offset:224
	ds_read_b32 v21, v33 offset:228
	ds_read_b32 v22, v33 offset:232
	ds_read_b32 v23, v33 offset:252
	ds_read_b32 v24, v33 offset:256
	ds_read_b32 v25, v33 offset:260
	ds_read_b32 v26, v33 offset:264
	ds_read_b32 v27, v33 offset:284
	ds_read_b32 v28, v33 offset:288
	ds_read_b32 v29, v33 offset:292
	ds_read_b32 v30, v33 offset:296
	v_cndmask_b32_e64 v49, v239, v49, s[42:43]
	v_cndmask_b32_e64 v48, v239, v48, s[46:47]
	v_cndmask_b32_e64 v51, v239, v51, s[50:51]
	v_cndmask_b32_e64 v50, v239, v50, s[54:55]
	v_cndmask_b32_e64 v53, v239, v53, s[58:59]
	v_cndmask_b32_e64 v52, v239, v52, s[62:63]
	v_cndmask_b32_e64 v55, v239, v55, s[66:67]
	v_cndmask_b32_e64 v54, v239, v54, s[70:71]
	v_cndmask_b32_e64 v57, v239, v57, s[74:75]
	v_cndmask_b32_e64 v56, v239, v56, s[78:79]
	v_cndmask_b32_e64 v59, v239, v59, s[82:83]
	v_cndmask_b32_e64 v58, v239, v58, s[86:87]
	v_cndmask_b32_e64 v61, v239, v61, s[90:91]
	v_cndmask_b32_e64 v60, v239, v60, s[94:95]
	v_cndmask_b32_e64 v63, v239, v63, s[4:5]
	v_cndmask_b32_e64 v62, v239, v62, s[8:9]
	s_waitcnt lgkmcnt(14)
	v_add_f32_e32 v0, v0, v32
	v_cndmask_b32_e64 v46, v239, v0, s[44:45]
	v_add_f32_e32 v0, v1, v16
	v_cndmask_b32_e64 v47, v239, v0, s[48:49]
	s_waitcnt lgkmcnt(13)
	v_add_f32_e32 v0, v2, v17
	v_cndmask_b32_e64 v44, v239, v0, s[52:53]
	s_waitcnt lgkmcnt(12)
	v_add_f32_e32 v0, v3, v18
	v_cndmask_b32_e64 v45, v239, v0, s[56:57]
	s_waitcnt lgkmcnt(11)
	v_add_f32_e32 v0, v4, v19
	v_cndmask_b32_e64 v42, v239, v0, s[60:61]
	s_waitcnt lgkmcnt(10)
	v_add_f32_e32 v0, v5, v20
	v_cndmask_b32_e64 v43, v239, v0, s[64:65]
	s_waitcnt lgkmcnt(9)
	v_add_f32_e32 v0, v6, v21
	v_cndmask_b32_e64 v40, v239, v0, s[68:69]
	s_waitcnt lgkmcnt(8)
	v_add_f32_e32 v0, v7, v22
	v_cndmask_b32_e64 v41, v239, v0, s[72:73]
	s_waitcnt lgkmcnt(7)
	v_add_f32_e32 v0, v8, v23
	v_cndmask_b32_e64 v38, v239, v0, s[76:77]
	s_waitcnt lgkmcnt(6)
	v_add_f32_e32 v0, v9, v24
	v_cndmask_b32_e64 v39, v239, v0, s[80:81]
	s_waitcnt lgkmcnt(5)
	v_add_f32_e32 v0, v10, v25
	v_cndmask_b32_e64 v32, v239, v0, s[84:85]
	s_waitcnt lgkmcnt(4)
	v_add_f32_e32 v0, v11, v26
	v_cndmask_b32_e64 v33, v239, v0, s[88:89]
	s_waitcnt lgkmcnt(3)
	v_add_f32_e32 v0, v12, v27
	v_cndmask_b32_e64 v34, v239, v0, s[92:93]
	s_waitcnt lgkmcnt(2)
	v_add_f32_e32 v0, v13, v28
	v_cndmask_b32_e64 v35, v239, v0, s[96:97]
	s_waitcnt lgkmcnt(1)
	v_add_f32_e32 v0, v14, v29
	v_cndmask_b32_e64 v36, v239, v0, s[6:7]
	s_waitcnt lgkmcnt(0)
	v_add_f32_e32 v0, v15, v30
	v_cndmask_b32_e64 v37, v239, v0, s[10:11]

; #define SBAR() __builtin_amdgcn_sched_barrier(0)
; #define NAM(P0, P1, t) do { if constexpr (NA) na_mask(P0, P1, kr_lo + (t), r0, qrow, qc, c0, hi, bl); } while (0)
; #define NAM(P0, P1, t) do { if constexpr (NA) na_mask(P0, P1, kr_lo + (t), r0, qrow, qc, c0, hi, bl); } while (0)
; template <bool QL>
; __device__ __forceinline__ void qkt(f32x16& p0, f32x16& p1, const bf16* Ks, const bf16x8* qr, const char* ql, int r32, int hi) {
;   p0 = f32x16{}; p1 = f32x16{};
;   for (int d0 = 0; d0 < 8; ++d0) { int cb = (d0 * 16 + hi * 8) * 2;
;     bf16x8 b0 = *reinterpret_cast<const bf16x8*>((const char*)Ks + KSWZ(r32, cb));
;     bf16x8 b1 = *reinterpret_cast<const bf16x8*>((const char*)Ks + KSWZ(32 + r32, cb));
;     bf16x8 q; if constexpr (QL) q = *reinterpret_cast<const bf16x8*>(ql + d0 * 1024); else q = qr[d0];
;     p0 = __builtin_amdgcn_mfma_f32_32x32x16_bf16(b0, q, p0, 0, 0, 0);
;     p1 = __builtin_amdgcn_mfma_f32_32x32x16_bf16(b1, q, p1, 0, 0, 0); }
; }
; __device__ __forceinline__ void na_mask(f32x16& p0, f32x16& p1, int kr, int r0, int qrow, int qc, int c0, int hi, const float* bl) {
;   const bool tv = (kr >= r0) && (kr < r0 + 8);
; template <bool NA, int ROWB>
; __device__ __forceinline__ void attn_dma(const bf16* __restrict__ Qb, const bf16* __restrict__ Kh, const bf16* __restrict__ Vh, bf16* __restrict__ Ob, int NT, char* lds, const int tid, float* __restrict__ ssb, int qrow0, int kr_lo, const float* bl) {
;     ...
;   for (int t = 1; t + 1 < NT; t += 2) {
;     DMA_TILE(t + 1, bn);
;     SBAR(); qkt<false>(pB0, pB1, (const bf16*)(K_lds + bc * SHM_K), qr, nullptr, r32, hi); NAM(pB0, pB1, t);
.LBB0_182:
	s_lshl_b32 s39, s17, 14
	s_add_i32 s1, s39, 0
	v_lshl_add_u64 v[160:161], s[28:29], 0, v[132:133]
	s_mov_b64 s[18:19], 0x1f520800
	s_add_i32 s14, s1, s33
	v_lshl_add_u64 v[64:65], v[160:161], 0, s[18:19]
	s_add_i32 m0, s14, 0xc000
	v_lshl_add_u64 v[162:163], s[28:29], 0, v[134:135]
	s_mov_b64 vcc, 0x1f521000
	global_load_lds_dwordx4 v[64:65], off
	v_lshl_add_u64 v[64:65], v[162:163], 0, vcc
	s_mov_b32 m0, s14
	v_lshl_add_u64 v[164:165], s[28:29], 0, v[136:137]
	global_load_lds_dwordx4 v[64:65], off
	v_lshl_add_u64 v[64:65], v[164:165], 0, s[18:19]
	s_add_i32 m0, s14, 0xc400
	v_lshl_add_u64 v[166:167], s[28:29], 0, v[142:143]
	global_load_lds_dwordx4 v[64:65], off
	v_lshl_add_u64 v[64:65], v[166:167], 0, vcc
	s_add_i32 m0, s14, 0x400
	s_nop 0
	global_load_lds_dwordx4 v[64:65], off
	s_lshl_b32 s30, s0, 14
	s_add_i32 s0, s30, 0
	v_add_u32_e32 v68, s0, v173
	ds_read_b128 v[64:67], v68 offset:49152
	ds_read_b128 v[68:71], v68 offset:57344
	v_add_u32_e32 v195, s0, v174
	ds_read_b128 v[196:199], v195 offset:49152
	ds_read_b128 v[222:225], v195 offset:57344
	v_add_u32_e32 v195, s0, v175
	s_waitcnt lgkmcnt(0)
	s_setprio 1
	v_mfma_f32_32x32x16_bf16 v[80:95], v[64:67], v[100:103], 0
	s_add_i32 s22, s37, s27
	v_mov_b32_e32 v241, 0xf149f2ca
	v_mov_b32_e32 v242, 0xf149f2ca
	v_mov_b32_e32 v243, 0xf149f2ca
	v_mov_b32_e32 v246, 0xf149f2ca
	v_mov_b32_e32 v247, 0xf149f2ca
	v_mov_b32_e32 v248, 0xf149f2ca
	v_mfma_f32_32x32x16_bf16 v[64:79], v[68:71], v[100:103], 0
	v_mov_b32_e32 v249, 0xf149f2ca
	v_mov_b32_e32 v250, 0xf149f2ca
	v_mov_b32_e32 v251, 0xf149f2ca
	v_mov_b32_e32 v237, 0xf149f2ca
	v_mov_b32_e32 v235, 0xf149f2ca
	v_mov_b32_e32 v203, 0xf149f2ca
	v_mov_b32_e32 v244, 0xf149f2ca
	v_mfma_f32_32x32x16_bf16 v[80:95], v[196:199], v[126:129], v[80:95]
	v_mov_b32_e32 v245, 0xf149f2ca
	v_mov_b32_e32 v238, 0xf149f2ca
	v_mov_b32_e32 v240, 0xf149f2ca
	v_mov_b32_e32 v234, 0xf149f2ca
	v_mov_b32_e32 v236, 0xf149f2ca
	v_mov_b32_e32 v230, 0xf149f2ca
	v_mov_b32_e32 v232, 0xf149f2ca
	v_mfma_f32_32x32x16_bf16 v[64:79], v[222:225], v[126:129], v[64:79]
	ds_read_b128 v[196:199], v195 offset:49152
	ds_read_b128 v[222:225], v195 offset:57344
	v_add_u32_e32 v195, s0, v176
	v_mov_b32_e32 v228, 0xf149f2ca
	v_mov_b32_e32 v229, 0xf149f2ca
	v_mov_b32_e32 v226, 0xf149f2ca
	v_mov_b32_e32 v221, 0xf149f2ca
	s_waitcnt lgkmcnt(0)
	v_mfma_f32_32x32x16_bf16 v[80:95], v[196:199], v[122:125], v[80:95]
	v_mfma_f32_32x32x16_bf16 v[64:79], v[222:225], v[122:125], v[64:79]
	ds_read_b128 v[196:199], v195 offset:49152
	ds_read_b128 v[222:225], v195 offset:57344
	v_add_u32_e32 v195, s0, v177
	s_waitcnt lgkmcnt(0)
	v_mfma_f32_32x32x16_bf16 v[80:95], v[196:199], v[118:121], v[80:95]
	v_mfma_f32_32x32x16_bf16 v[64:79], v[222:225], v[118:121], v[64:79]
	ds_read_b128 v[196:199], v195 offset:49152
	ds_read_b128 v[222:225], v195 offset:57344
	v_add_u32_e32 v195, s0, v178
	s_waitcnt lgkmcnt(0)
	v_mfma_f32_32x32x16_bf16 v[80:95], v[196:199], v[114:117], v[80:95]
	v_mfma_f32_32x32x16_bf16 v[64:79], v[222:225], v[114:117], v[64:79]
	ds_read_b128 v[196:199], v195 offset:49152
	ds_read_b128 v[222:225], v195 offset:57344
	v_add_u32_e32 v195, s0, v179
	s_waitcnt lgkmcnt(0)
	v_mfma_f32_32x32x16_bf16 v[80:95], v[196:199], v[108:111], v[80:95]
	v_mfma_f32_32x32x16_bf16 v[64:79], v[222:225], v[108:111], v[64:79]
	ds_read_b128 v[196:199], v195 offset:49152
	ds_read_b128 v[222:225], v195 offset:57344
	v_add_u32_e32 v195, s0, v180
	s_add_i32 s0, s22, -6
	v_cmp_ge_u32_e32 vcc, s0, v190
	v_cmp_lt_u32_e64 s[18:19], s0, v191
	s_and_b64 s[14:15], vcc, s[18:19]
	s_waitcnt lgkmcnt(0)
	v_mfma_f32_32x32x16_bf16 v[80:95], v[196:199], v[104:107], v[80:95]
	v_mfma_f32_32x32x16_bf16 v[64:79], v[222:225], v[104:107], v[64:79]
	ds_read_b128 v[196:199], v195 offset:49152
	ds_read_b128 v[222:225], v195 offset:57344
	s_waitcnt lgkmcnt(0)
	v_mfma_f32_32x32x16_bf16 v[80:95], v[196:199], v[96:99], v[80:95]
	v_mov_b32_e32 v196, 0xf149f2ca
	v_mov_b32_e32 v197, 0xf149f2ca
	v_mov_b32_e32 v198, 0xf149f2ca
	v_mov_b32_e32 v199, 0xf149f2ca
	v_mfma_f32_32x32x16_bf16 v[64:79], v[222:225], v[96:99], v[64:79]
	s_setprio 0
	v_mov_b32_e32 v225, 0xf149f2ca
	v_mov_b32_e32 v223, 0xf149f2ca
	v_mov_b32_e32 v224, 0xf149f2ca
	v_mov_b32_e32 v222, 0xf149f2ca
	s_and_saveexec_b64 s[18:19], s[14:15]
	s_cbranch_execz .LBB0_216
; #define SBAR() __builtin_amdgcn_sched_barrier(0)
; __device__ __forceinline__ void finishSM(f32x16& p0, f32x16& p1, float alpha, float& l_reg, bf16x8& pa0, bf16x8& pa1, bf16x8& pa2, bf16x8& pa3) {
;   for (int r = 0; r < 16; ++r) p1[r] = __builtin_amdgcn_exp2f(p1[r]);
;   float ps = 0; for (int r = 0; r < 16; ++r) ps += p0[r]; for (int r = 0; r < 16; ++r) ps += p1[r];
;   { auto rr = __builtin_amdgcn_permlane32_swap(__float_as_uint(ps), __float_as_uint(ps), false, false);
;     ps = __uint_as_float(rr[0]) + __uint_as_float(rr[1]); }
;   l_reg = l_reg * alpha + ps;
;     ...
;   PK4(p0, 0, pa0); PK4(p0, 8, pa1); PK4(p1, 0, pa2); PK4(p1, 8, pa3);
; __device__ __forceinline__ void na_mask(f32x16& p0, f32x16& p1, int kr, int r0, int qrow, int qc, int c0, int hi, const float* bl) {
;     ...
;   } else {
;     const float* brow = bl + (kr - qrow + 7) * 31 + 15 - qc + 4 * hi;
;     const int d = 4 * hi - c0;
; #pragma unroll
;     for (int r = 0; r < 16; ++r) {
;       const int kc = (r & 3) + 8 * (r >> 2);
;       const float b0 = brow[kc], b1 = brow[kc + 32];
;       p0[r] = (unsigned)(d + kc) < 16u ? p0[r] + b0 : -1e30f; p1[r] = (unsigned)(d + kc + 32) < 16u ? p1[r] + b1 : -1e30f;
;     }
;   }
; template <int OFF> __device__ __forceinline__ s16x4 tr_read(int vb) {
;   s16x4 r; asm volatile("ds_read_b64_tr_b16 %0, %1 offset:%2" : "=&v"(r) : "v"(vb), "i"(OFF) : "memory"); return r;
; }
; template <int D0> __device__ __forceinline__ void pv_one(f32x16& od, int vb, bf16x8 pa0, bf16x8 pa1, bf16x8 pa2, bf16x8 pa3) {
;   const s16x4 l0 = tr_read<v_rd_off(D0, 0, 0)>(vb), h0 = tr_read<v_rd_off(D0, 0, 1)>(vb), l1 = tr_read<v_rd_off(D0, 1, 0)>(vb), h1 = tr_read<v_rd_off(D0, 1, 1)>(vb);
;   const s16x4 l2 = tr_read<v_rd_off(D0, 2, 0)>(vb), h2 = tr_read<v_rd_off(D0, 2, 1)>(vb), l3 = tr_read<v_rd_off(D0, 3, 0)>(vb), h3 = tr_read<v_rd_off(D0, 3, 1)>(vb);
;   asm volatile("s_waitcnt lgkmcnt(0)" ::: "memory"); SBAR();
	ds_read_b32 v195, v193 offset:128
	v_mov_b32_e32 v221, 0xf149f2ca
	v_mov_b32_e32 v222, 0xf149f2ca
	v_mov_b32_e32 v223, 0xf149f2ca
	v_mov_b32_e32 v224, 0xf149f2ca
	v_mov_b32_e32 v225, 0xf149f2ca
	v_mov_b32_e32 v226, 0xf149f2ca
	v_mov_b32_e32 v228, 0xf149f2ca
	v_mov_b32_e32 v229, 0xf149f2ca
	v_mov_b32_e32 v230, 0xf149f2ca
	v_mov_b32_e32 v232, 0xf149f2ca
	v_mov_b32_e32 v234, 0xf149f2ca
	v_mov_b32_e32 v236, 0xf149f2ca
	v_mov_b32_e32 v238, 0xf149f2ca
	v_mov_b32_e32 v240, 0xf149f2ca
	v_mov_b32_e32 v244, 0xf149f2ca
	v_mov_b32_e32 v245, 0xf149f2ca
	ds_read_b32 v222, v193
	ds_read_b32 v221, v193 offset:4
	ds_read_b32 v224, v193 offset:8
	ds_read_b32 v223, v193 offset:12
	ds_read_b32 v226, v193 offset:32
	ds_read_b32 v225, v193 offset:36
	ds_read_b32 v229, v193 offset:40
	ds_read_b32 v228, v193 offset:44
	ds_read_b32 v232, v193 offset:64
	ds_read_b32 v230, v193 offset:68
	ds_read_b32 v236, v193 offset:72
	ds_read_b32 v234, v193 offset:76
	ds_read_b32 v240, v193 offset:96
	ds_read_b32 v238, v193 offset:100
	ds_read_b32 v245, v193 offset:104
	ds_read_b32 v244, v193 offset:108
	s_waitcnt lgkmcnt(0)
	v_add_f32_e32 v222, v80, v222
	v_add_f32_e32 v221, v81, v221
	v_add_f32_e32 v224, v82, v224
	v_add_f32_e32 v223, v83, v223
	v_add_f32_e32 v226, v84, v226
	v_add_f32_e32 v225, v85, v225
	v_add_f32_e32 v229, v86, v229
	v_add_f32_e32 v228, v87, v228
	v_add_f32_e32 v232, v88, v232
	v_add_f32_e32 v230, v89, v230
	v_add_f32_e32 v236, v90, v236
	v_add_f32_e32 v234, v91, v234
	v_add_f32_e32 v240, v92, v240
	v_add_f32_e32 v238, v93, v238
	v_add_f32_e32 v245, v94, v245
	v_add_f32_e32 v244, v95, v244
	ds_read_b32 v80, v193 offset:132
	ds_read_b32 v81, v193 offset:136
	ds_read_b32 v82, v193 offset:140
	ds_read_b32 v83, v193 offset:160
	ds_read_b32 v84, v193 offset:164
	ds_read_b32 v85, v193 offset:168
	ds_read_b32 v86, v193 offset:172
	ds_read_b32 v87, v193 offset:192
	ds_read_b32 v88, v193 offset:196
	ds_read_b32 v89, v193 offset:200
	ds_read_b32 v90, v193 offset:204
	ds_read_b32 v91, v193 offset:224
	ds_read_b32 v92, v193 offset:228
	ds_read_b32 v196, v193 offset:232
	ds_read_b32 v93, v193 offset:236
	v_cndmask_b32_e64 v222, v239, v222, s[42:43]
	v_cndmask_b32_e64 v221, v239, v221, s[46:47]
	v_cndmask_b32_e64 v224, v239, v224, s[50:51]
	v_cndmask_b32_e64 v223, v239, v223, s[54:55]
	v_cndmask_b32_e64 v226, v239, v226, s[58:59]
	v_cndmask_b32_e64 v225, v239, v225, s[62:63]
	v_cndmask_b32_e64 v229, v239, v229, s[66:67]
	v_cndmask_b32_e64 v228, v239, v228, s[70:71]
	v_cndmask_b32_e64 v232, v239, v232, s[74:75]
	v_cndmask_b32_e64 v230, v239, v230, s[78:79]
	v_cndmask_b32_e64 v236, v239, v236, s[82:83]
	v_cndmask_b32_e64 v234, v239, v234, s[86:87]
	v_cndmask_b32_e64 v240, v239, v240, s[90:91]
	v_cndmask_b32_e64 v238, v239, v238, s[94:95]
	v_cndmask_b32_e64 v245, v239, v245, s[4:5]
	v_cndmask_b32_e64 v244, v239, v244, s[8:9]
	s_waitcnt lgkmcnt(0)
	v_add_f32_e32 v64, v64, v195
	v_add_f32_e32 v78, v78, v196
	v_add_f32_e32 v77, v77, v92
	v_add_f32_e32 v76, v76, v91
	v_add_f32_e32 v75, v75, v90
	v_add_f32_e32 v74, v74, v89
	v_add_f32_e32 v73, v73, v88
	v_add_f32_e32 v72, v72, v87
	v_add_f32_e32 v71, v71, v86
	v_add_f32_e32 v70, v70, v85
	v_add_f32_e32 v69, v69, v84
	v_add_f32_e32 v68, v68, v83
	v_add_f32_e32 v67, v67, v82
	v_add_f32_e32 v66, v66, v81
	v_add_f32_e32 v65, v65, v80
	v_cndmask_b32_e64 v198, v239, v64, s[44:45]
	v_add_f32_e32 v64, v79, v93
	v_cndmask_b32_e64 v241, v239, v78, s[6:7]
	v_cndmask_b32_e64 v242, v239, v77, s[96:97]
	v_cndmask_b32_e64 v243, v239, v76, s[92:93]
	v_cndmask_b32_e64 v246, v239, v75, s[88:89]
	v_cndmask_b32_e64 v247, v239, v74, s[84:85]
	v_cndmask_b32_e64 v248, v239, v73, s[80:81]
	v_cndmask_b32_e64 v249, v239, v72, s[76:77]
	v_cndmask_b32_e64 v250, v239, v71, s[72:73]
	v_cndmask_b32_e64 v251, v239, v70, s[68:69]
	v_cndmask_b32_e64 v237, v239, v69, s[64:65]
	v_cndmask_b32_e64 v235, v239, v68, s[60:61]
	v_cndmask_b32_e64 v203, v239, v67, s[56:57]
	v_cndmask_b32_e64 v196, v239, v66, s[52:53]
	v_cndmask_b32_e64 v197, v239, v65, s[48:49]
	v_cndmask_b32_e64 v199, v239, v64, s[10:11]
.LBB0_216:
	s_or_b64 exec, exec, s[18:19]
	s_nop 4
	v_add_f32_e32 v64, 0, v213
	v_add_f32_e32 v64, v217, v64
	v_add_f32_e32 v64, v214, v64
	v_add_f32_e32 v64, v218, v64
	v_add_f32_e32 v64, v215, v64
	v_add_f32_e32 v64, v219, v64
	v_add_f32_e32 v64, v216, v64
	v_add_f32_e32 v64, v220, v64
	v_add_f32_e32 v64, v205, v64
	v_add_f32_e32 v64, v209, v64
	v_add_f32_e32 v64, v206, v64
	v_add_f32_e32 v64, v210, v64
	v_exp_f32_e32 v72, v144
	v_add_f32_e32 v64, v207, v64
	v_exp_f32_e32 v73, v145
	v_add_f32_e32 v64, v211, v64
	v_exp_f32_e32 v74, v146
	v_add_f32_e32 v64, v208, v64
	v_exp_f32_e32 v75, v147
	v_add_f32_e32 v64, v212, v64
	v_exp_f32_e32 v76, v148
	v_add_f32_e32 v64, v72, v64
	v_exp_f32_e32 v77, v149
	v_add_f32_e32 v64, v73, v64
	v_exp_f32_e32 v78, v150
	v_add_f32_e32 v64, v74, v64
	v_exp_f32_e32 v79, v151
	v_add_f32_e32 v64, v75, v64
	v_exp_f32_e32 v80, v152
	v_add_f32_e32 v64, v76, v64
	v_exp_f32_e32 v81, v153
	v_add_f32_e32 v64, v77, v64
	v_exp_f32_e32 v82, v154
	v_add_f32_e32 v64, v78, v64
	v_exp_f32_e32 v83, v155
	v_add_f32_e32 v64, v79, v64
	v_exp_f32_e32 v84, v156
	v_add_f32_e32 v64, v80, v64
	v_exp_f32_e32 v85, v157
	v_add_f32_e32 v64, v81, v64
	v_exp_f32_e32 v86, v158
	v_add_f32_e32 v64, v82, v64
	v_exp_f32_e32 v87, v159
	v_add_f32_e32 v64, v83, v64
	v_add_f32_e32 v64, v84, v64
	v_add_f32_e32 v64, v85, v64
	v_add_f32_e32 v64, v86, v64
	v_add_f32_e32 v195, v87, v64
	v_mov_b32_e32 v204, v195
	s_nop 1
	v_permlane32_swap_b32_e32 v195, v204
	v_cvt_pk_bf16_f32 v64, v213, v217
	v_cvt_pk_bf16_f32 v65, v214, v218
	v_cvt_pk_bf16_f32 v66, v215, v219
	v_cvt_pk_bf16_f32 v67, v216, v220
	v_cvt_pk_bf16_f32 v68, v205, v209
	v_cvt_pk_bf16_f32 v69, v206, v210
	v_cvt_pk_bf16_f32 v70, v207, v211
	v_cvt_pk_bf16_f32 v71, v208, v212
	v_cvt_pk_bf16_f32 v72, v72, v73
	v_cvt_pk_bf16_f32 v73, v74, v75
	v_cvt_pk_bf16_f32 v74, v76, v77
	v_cvt_pk_bf16_f32 v75, v78, v79
	v_cvt_pk_bf16_f32 v76, v80, v81
	v_cvt_pk_bf16_f32 v77, v82, v83
	v_cvt_pk_bf16_f32 v78, v84, v85
	v_cvt_pk_bf16_f32 v79, v86, v87
	s_nop 0
	v_permlane32_swap_b32_e32 v64, v66
	v_permlane32_swap_b32_e32 v65, v67
	v_permlane32_swap_b32_e32 v68, v70
	v_permlane32_swap_b32_e32 v69, v71
	v_permlane32_swap_b32_e32 v72, v74
	v_permlane32_swap_b32_e32 v73, v75
	v_permlane32_swap_b32_e32 v76, v78
	v_permlane32_swap_b32_e32 v77, v79
	v_lshl_add_u32 v144, s23, 14, v171
	ds_read_b64_tr_b16 v[80:81], v144 offset:0
	ds_read_b64_tr_b16 v[82:83], v144 offset:0x800
	ds_read_b64_tr_b16 v[84:85], v144 offset:0x1000
	ds_read_b64_tr_b16 v[86:87], v144 offset:0x1800
	ds_read_b64_tr_b16 v[88:89], v144 offset:0x2000
	ds_read_b64_tr_b16 v[90:91], v144 offset:0x2800
	ds_read_b64_tr_b16 v[92:93], v144 offset:0x3000
	ds_read_b64_tr_b16 v[94:95], v144 offset:0x3800
	s_waitcnt lgkmcnt(0)
; #define SBAR() __builtin_amdgcn_sched_barrier(0)
; __device__ __forceinline__ void partialSM(f32x16& p0, f32x16& p1, float& m_reg, float& mn, float& alpha) {
;   constexpr float C = SCALE * 1.4426950408889634f;
;   float pmax = p0[0]; for (int r = 1; r < 16; ++r) pmax = fmaxf(pmax, p0[r]); for (int r = 0; r < 16; ++r) pmax = fmaxf(pmax, p1[r]);
;   { auto rr = __builtin_amdgcn_permlane32_swap(__float_as_uint(pmax), __float_as_uint(pmax), false, false);
;     pmax = fmaxf(__uint_as_float(rr[0]), __uint_as_float(rr[1])); }
;   if (__builtin_expect(__all(pmax - m_reg <= THR / SCALE), 1)) { mn = m_reg; alpha = 1.f; }
;   else { mn = fmaxf(m_reg, pmax); alpha = __builtin_amdgcn_exp2f((m_reg - mn) * C); m_reg = mn; }
;   float mnC = -mn * C;
;   for (int r = 0; r < 16; ++r) p0[r] = fmaf(p0[r], C, mnC); for (int r = 0; r < 16; ++r) p1[r] = fmaf(p1[r], C, mnC);
; template <int D0> __device__ __forceinline__ void pv_one(f32x16& od, int vb, bf16x8 pa0, bf16x8 pa1, bf16x8 pa2, bf16x8 pa3) {
;   const s16x4 l0 = tr_read<v_rd_off(D0, 0, 0)>(vb), h0 = tr_read<v_rd_off(D0, 0, 1)>(vb), l1 = tr_read<v_rd_off(D0, 1, 0)>(vb), h1 = tr_read<v_rd_off(D0, 1, 1)>(vb);
;   const s16x4 l2 = tr_read<v_rd_off(D0, 2, 0)>(vb), h2 = tr_read<v_rd_off(D0, 2, 1)>(vb), l3 = tr_read<v_rd_off(D0, 3, 0)>(vb), h3 = tr_read<v_rd_off(D0, 3, 1)>(vb);
;   asm volatile("s_waitcnt lgkmcnt(0)" ::: "memory"); SBAR();
;     ...
;   od = __builtin_amdgcn_mfma_f32_32x32x16_bf16(pa0, PK(l0, h0), od, 0, 0, 0);
;   od = __builtin_amdgcn_mfma_f32_32x32x16_bf16(pa1, PK(l1, h1), od, 0, 0, 0);
;   od = __builtin_amdgcn_mfma_f32_32x32x16_bf16(pa2, PK(l2, h2), od, 0, 0, 0);
;   od = __builtin_amdgcn_mfma_f32_32x32x16_bf16(pa3, PK(l3, h3), od, 0, 0, 0);
;     ...
; }
; __device__ __forceinline__ void pv_d0(f32x16* o, int vb, bf16x8 pa0, bf16x8 pa1, bf16x8 pa2, bf16x8 pa3) {
;   pv_one<0>(o[0], vb, pa0, pa1, pa2, pa3); pv_one<1>(o[1], vb, pa0, pa1, pa2, pa3); pv_one<2>(o[2], vb, pa0, pa1, pa2, pa3); pv_one<3>(o[3], vb, pa0, pa1, pa2, pa3);
	s_nop 0
	s_setprio 1
	v_mfma_f32_32x32x16_bf16 v[0:15], v[64:67], v[80:83], v[0:15]
	ds_read_b64_tr_b16 v[80:81], v144 offset:0x200
	ds_read_b64_tr_b16 v[82:83], v144 offset:0xa00
	v_mfma_f32_32x32x16_bf16 v[0:15], v[68:71], v[84:87], v[0:15]
	ds_read_b64_tr_b16 v[84:85], v144 offset:0x1200
	ds_read_b64_tr_b16 v[86:87], v144 offset:0x1a00
	v_mfma_f32_32x32x16_bf16 v[0:15], v[72:75], v[88:91], v[0:15]
	ds_read_b64_tr_b16 v[88:89], v144 offset:0x2200
	ds_read_b64_tr_b16 v[90:91], v144 offset:0x2a00
	v_mfma_f32_32x32x16_bf16 v[0:15], v[76:79], v[92:95], v[0:15]
	ds_read_b64_tr_b16 v[92:93], v144 offset:0x3200
	ds_read_b64_tr_b16 v[94:95], v144 offset:0x3a00
	s_waitcnt lgkmcnt(0)
	v_mfma_f32_32x32x16_bf16 v[48:63], v[64:67], v[80:83], v[48:63]
	ds_read_b64_tr_b16 v[80:81], v144 offset:0x400
	ds_read_b64_tr_b16 v[82:83], v144 offset:0xc00
	v_mfma_f32_32x32x16_bf16 v[48:63], v[68:71], v[84:87], v[48:63]
	ds_read_b64_tr_b16 v[84:85], v144 offset:0x1400
	ds_read_b64_tr_b16 v[86:87], v144 offset:0x1c00
	v_mfma_f32_32x32x16_bf16 v[48:63], v[72:75], v[88:91], v[48:63]
	ds_read_b64_tr_b16 v[88:89], v144 offset:0x2400
	ds_read_b64_tr_b16 v[90:91], v144 offset:0x2c00
	v_mfma_f32_32x32x16_bf16 v[48:63], v[76:79], v[92:95], v[48:63]
	ds_read_b64_tr_b16 v[92:93], v144 offset:0x3400
	ds_read_b64_tr_b16 v[94:95], v144 offset:0x3c00
	s_waitcnt lgkmcnt(0)
	v_mfma_f32_32x32x16_bf16 v[32:47], v[64:67], v[80:83], v[32:47]
	ds_read_b64_tr_b16 v[80:81], v144 offset:0x600
	ds_read_b64_tr_b16 v[82:83], v144 offset:0xe00
	v_mfma_f32_32x32x16_bf16 v[32:47], v[68:71], v[84:87], v[32:47]
	ds_read_b64_tr_b16 v[84:85], v144 offset:0x1600
	ds_read_b64_tr_b16 v[86:87], v144 offset:0x1e00
	v_mfma_f32_32x32x16_bf16 v[32:47], v[72:75], v[88:91], v[32:47]
	ds_read_b64_tr_b16 v[88:89], v144 offset:0x2600
	ds_read_b64_tr_b16 v[90:91], v144 offset:0x2e00
	v_mfma_f32_32x32x16_bf16 v[32:47], v[76:79], v[92:95], v[32:47]
	ds_read_b64_tr_b16 v[92:93], v144 offset:0x3600
	ds_read_b64_tr_b16 v[94:95], v144 offset:0x3e00
	s_waitcnt lgkmcnt(0)
	v_mfma_f32_32x32x16_bf16 v[16:31], v[64:67], v[80:83], v[16:31]
	v_max_f32_e32 v64, v221, v221
	v_max_f32_e32 v65, v222, v222
	v_max_f32_e32 v64, v65, v64
	v_max3_f32 v64, v64, v224, v223
	v_max3_f32 v64, v64, v226, v225
	v_max3_f32 v64, v64, v229, v228
	v_max3_f32 v64, v64, v232, v230
	v_max3_f32 v64, v64, v236, v234
	v_max3_f32 v64, v64, v240, v238
	v_mfma_f32_32x32x16_bf16 v[16:31], v[68:71], v[84:87], v[16:31]
	v_max3_f32 v64, v64, v245, v244
	v_max3_f32 v64, v64, v198, v197
	v_max3_f32 v64, v64, v196, v203
	v_max3_f32 v64, v64, v235, v237
	v_max3_f32 v64, v64, v251, v250
	v_max3_f32 v64, v64, v249, v248
	v_max3_f32 v64, v64, v247, v246
	v_max3_f32 v64, v64, v243, v242
	v_mfma_f32_32x32x16_bf16 v[16:31], v[72:75], v[88:91], v[16:31]
	v_max3_f32 v64, v64, v241, v199
	v_mov_b32_e32 v65, v64
	s_nop 1
	v_permlane32_swap_b32_e32 v64, v65
	v_max_f32_e32 v65, v65, v65
	v_max_f32_e32 v64, v64, v64
	v_max_f32_e32 v64, v64, v65
	v_sub_f32_e32 v65, v64, v192
	s_mov_b32 s0, 0x42b504f3
	v_cmp_ge_f32_e32 vcc, s0, v65
	v_max_f32_e32 v65, v192, v192
	v_max_f32_e32 v214, v65, v64
	v_mfma_f32_32x32x16_bf16 v[16:31], v[76:79], v[92:95], v[16:31]
	s_setprio 0
	v_sub_f32_e32 v64, v192, v214
	v_mul_f32_e32 v64, 0x3e0293ee, v64
	v_exp_f32_e32 v64, v64
	s_cmp_eq_u64 vcc, exec
	s_cselect_b64 s[18:19], -1, 0
	v_cndmask_b32_e64 v227, v64, 1.0, s[18:19]
	v_cmp_gt_f32_e32 vcc, 1.0, v227
	s_cbranch_vccz .LBB0_220
	s_and_saveexec_b64 s[14:15], s[12:13]
	ds_write_b32 v181, v227 offset:128
	s_or_b64 exec, exec, s[14:15]
	s_waitcnt lgkmcnt(0)
	v_add_u32_e32 v76, v169, v172
	ds_read_b128 v[64:67], v76 offset:224
	ds_read_b128 v[68:71], v76 offset:192
	ds_read_b128 v[72:75], v76 offset:160
	ds_read_b128 v[76:79], v76 offset:128
	s_waitcnt lgkmcnt(0)
	v_pk_mul_f32 v[12:13], v[12:13], v[64:65]
	v_pk_mul_f32 v[8:9], v[8:9], v[68:69]
	v_pk_mul_f32 v[4:5], v[4:5], v[72:73]
	v_pk_mul_f32 v[14:15], v[14:15], v[66:67]
	v_pk_mul_f32 v[10:11], v[10:11], v[70:71]
	v_pk_mul_f32 v[6:7], v[6:7], v[74:75]
	v_pk_mul_f32 v[2:3], v[2:3], v[78:79]
	v_pk_mul_f32 v[0:1], v[0:1], v[76:77]
	v_pk_mul_f32 v[60:61], v[60:61], v[64:65]
	v_pk_mul_f32 v[56:57], v[56:57], v[68:69]
	v_pk_mul_f32 v[52:53], v[52:53], v[72:73]
	v_pk_mul_f32 v[62:63], v[62:63], v[66:67]
	v_pk_mul_f32 v[58:59], v[58:59], v[70:71]
	v_pk_mul_f32 v[54:55], v[54:55], v[74:75]
	v_pk_mul_f32 v[50:51], v[50:51], v[78:79]
	v_pk_mul_f32 v[48:49], v[48:49], v[76:77]
	v_pk_mul_f32 v[44:45], v[44:45], v[64:65]
	v_pk_mul_f32 v[40:41], v[40:41], v[68:69]
	v_pk_mul_f32 v[36:37], v[36:37], v[72:73]
	v_pk_mul_f32 v[46:47], v[46:47], v[66:67]
	v_pk_mul_f32 v[42:43], v[42:43], v[70:71]
	v_pk_mul_f32 v[38:39], v[38:39], v[74:75]
	v_pk_mul_f32 v[34:35], v[34:35], v[78:79]
	v_pk_mul_f32 v[32:33], v[32:33], v[76:77]
	v_pk_mul_f32 v[28:29], v[28:29], v[64:65]
	v_pk_mul_f32 v[24:25], v[24:25], v[68:69]
	v_pk_mul_f32 v[20:21], v[20:21], v[72:73]
	v_pk_mul_f32 v[30:31], v[30:31], v[66:67]
	v_pk_mul_f32 v[26:27], v[26:27], v[70:71]
	v_pk_mul_f32 v[22:23], v[22:23], v[74:75]
	v_pk_mul_f32 v[18:19], v[18:19], v[78:79]
	v_pk_mul_f32 v[16:17], v[16:17], v[76:77]

; #define SBAR() __builtin_amdgcn_sched_barrier(0)
; #define NAM(P0, P1, t) do { if constexpr (NA) na_mask(P0, P1, kr_lo + (t), r0, qrow, qc, c0, hi, bl); } while (0)
; #define NAM(P0, P1, t) do { if constexpr (NA) na_mask(P0, P1, kr_lo + (t), r0, qrow, qc, c0, hi, bl); } while (0)
; template <bool QL>
; __device__ __forceinline__ void qkt(f32x16& p0, f32x16& p1, const bf16* Ks, const bf16x8* qr, const char* ql, int r32, int hi) {
;   p0 = f32x16{}; p1 = f32x16{};
;   for (int d0 = 0; d0 < 8; ++d0) { int cb = (d0 * 16 + hi * 8) * 2;
;     bf16x8 b0 = *reinterpret_cast<const bf16x8*>((const char*)Ks + KSWZ(r32, cb));
;     bf16x8 b1 = *reinterpret_cast<const bf16x8*>((const char*)Ks + KSWZ(32 + r32, cb));
;     bf16x8 q; if constexpr (QL) q = *reinterpret_cast<const bf16x8*>(ql + d0 * 1024); else q = qr[d0];
;     p0 = __builtin_amdgcn_mfma_f32_32x32x16_bf16(b0, q, p0, 0, 0, 0);
;     p1 = __builtin_amdgcn_mfma_f32_32x32x16_bf16(b1, q, p1, 0, 0, 0); }
; }
; __device__ __forceinline__ void na_mask(f32x16& p0, f32x16& p1, int kr, int r0, int qrow, int qc, int c0, int hi, const float* bl) {
;   const bool tv = (kr >= r0) && (kr < r0 + 8);
;   if (!tv) {
; #pragma unroll
;     for (int r = 0; r < 16; ++r) { p0[r] = -1e30f; p1[r] = -1e30f; }
;   } else {
;     const float* brow = bl + (kr - qrow + 7) * 31 + 15 - qc + 4 * hi;
; template <bool NA, int ROWB>
; __device__ __forceinline__ void attn_dma(const bf16* __restrict__ Qb, const bf16* __restrict__ Kh, const bf16* __restrict__ Vh, bf16* __restrict__ Ob, int NT, char* lds, const int tid, float* __restrict__ ssb, int qrow0, int kr_lo, const float* bl) {
;     ...
;     bp = bc; bc = bn; bn = NEXTB(bn);
;     if (t + 2 < NT) DMA_TILE(t + 2, bn);
;     SBAR(); qkt<false>(pA0, pA1, (const bf16*)(K_lds + bc * SHM_K), qr, nullptr, r32, hi); NAM(pA0, pA1, t + 1);
.LBB0_222:
	v_add_u32_e32 v68, s1, v173
	ds_read_b128 v[64:67], v68 offset:49152
	v_add_u32_e32 v148, s1, v174
	ds_read_b128 v[144:147], v148 offset:49152
	s_waitcnt lgkmcnt(0)
	s_setprio 1
	v_mfma_f32_32x32x16_bf16 v[80:95], v[64:67], v[100:103], 0
	ds_read_b128 v[64:67], v68 offset:57344
	v_mfma_f32_32x32x16_bf16 v[80:95], v[144:147], v[126:129], v[80:95]
	ds_read_b128 v[144:147], v148 offset:57344
	v_add_u32_e32 v148, s1, v175
	s_waitcnt lgkmcnt(0)
	v_mfma_f32_32x32x16_bf16 v[64:79], v[64:67], v[100:103], 0
	v_mfma_f32_32x32x16_bf16 v[64:79], v[144:147], v[126:129], v[64:79]
	ds_read_b128 v[144:147], v148 offset:49152
	s_waitcnt lgkmcnt(0)
	v_mfma_f32_32x32x16_bf16 v[80:95], v[144:147], v[122:125], v[80:95]
	ds_read_b128 v[144:147], v148 offset:57344
	v_add_u32_e32 v148, s1, v176
	s_waitcnt lgkmcnt(0)
	v_mfma_f32_32x32x16_bf16 v[64:79], v[144:147], v[122:125], v[64:79]
	ds_read_b128 v[144:147], v148 offset:49152
	s_waitcnt lgkmcnt(0)
	v_mfma_f32_32x32x16_bf16 v[80:95], v[144:147], v[118:121], v[80:95]
	ds_read_b128 v[144:147], v148 offset:57344
	v_add_u32_e32 v148, s1, v177
	s_waitcnt lgkmcnt(0)
	v_mfma_f32_32x32x16_bf16 v[64:79], v[144:147], v[118:121], v[64:79]
	ds_read_b128 v[144:147], v148 offset:49152
	s_waitcnt lgkmcnt(0)
	v_mfma_f32_32x32x16_bf16 v[80:95], v[144:147], v[114:117], v[80:95]
	ds_read_b128 v[144:147], v148 offset:57344
	v_add_u32_e32 v148, s1, v178
	s_waitcnt lgkmcnt(0)
	v_mfma_f32_32x32x16_bf16 v[64:79], v[144:147], v[114:117], v[64:79]
	ds_read_b128 v[144:147], v148 offset:49152
	s_waitcnt lgkmcnt(0)
	v_mfma_f32_32x32x16_bf16 v[80:95], v[144:147], v[108:111], v[80:95]
	ds_read_b128 v[144:147], v148 offset:57344
	v_add_u32_e32 v148, s1, v179
	s_waitcnt lgkmcnt(0)
	v_mfma_f32_32x32x16_bf16 v[64:79], v[144:147], v[108:111], v[64:79]
	ds_read_b128 v[144:147], v148 offset:49152
	s_waitcnt lgkmcnt(0)
	v_mfma_f32_32x32x16_bf16 v[80:95], v[144:147], v[104:107], v[80:95]
	ds_read_b128 v[144:147], v148 offset:57344
	v_add_u32_e32 v148, s1, v180
	s_add_i32 s1, s22, -5
	v_cmp_lt_u32_e64 s[22:23], s1, v190
	v_cmp_ge_u32_e32 vcc, s1, v191
	s_or_b64 s[14:15], s[22:23], vcc
	s_waitcnt lgkmcnt(0)
	v_mfma_f32_32x32x16_bf16 v[64:79], v[144:147], v[104:107], v[64:79]
	ds_read_b128 v[144:147], v148 offset:49152
	s_waitcnt lgkmcnt(0)
	v_mfma_f32_32x32x16_bf16 v[80:95], v[144:147], v[96:99], v[80:95]
	ds_read_b128 v[144:147], v148 offset:57344
	s_waitcnt lgkmcnt(0)
	v_mfma_f32_32x32x16_bf16 v[64:79], v[144:147], v[96:99], v[64:79]
	s_setprio 0
	s_and_saveexec_b64 s[22:23], s[14:15]
	s_xor_b64 s[14:15], exec, s[22:23]
	s_or_saveexec_b64 s[22:23], s[14:15]
	v_mov_b32_e32 v158, 0xf149f2ca
	v_mov_b32_e32 v157, 0xf149f2ca
	v_mov_b32_e32 v156, 0xf149f2ca
	v_mov_b32_e32 v155, 0xf149f2ca
	v_mov_b32_e32 v154, 0xf149f2ca
	v_mov_b32_e32 v153, 0xf149f2ca
	v_mov_b32_e32 v152, 0xf149f2ca
	v_mov_b32_e32 v151, 0xf149f2ca
	v_mov_b32_e32 v150, 0xf149f2ca
	v_mov_b32_e32 v149, 0xf149f2ca
	v_mov_b32_e32 v148, 0xf149f2ca
	v_mov_b32_e32 v147, 0xf149f2ca
	v_mov_b32_e32 v146, 0xf149f2ca
	v_mov_b32_e32 v145, 0xf149f2ca
	v_mov_b32_e32 v144, 0xf149f2ca
	v_mov_b32_e32 v212, 0xf149f2ca
	v_mov_b32_e32 v213, 0xf149f2ca
	v_mov_b32_e32 v210, 0xf149f2ca
	v_mov_b32_e32 v211, 0xf149f2ca
	v_mov_b32_e32 v208, 0xf149f2ca
	v_mov_b32_e32 v209, 0xf149f2ca
	v_mov_b32_e32 v206, 0xf149f2ca
	v_mov_b32_e32 v207, 0xf149f2ca
	v_mov_b32_e32 v167, 0xf149f2ca
	v_mov_b32_e32 v205, 0xf149f2ca
	v_mov_b32_e32 v165, 0xf149f2ca
	v_mov_b32_e32 v166, 0xf149f2ca
	v_mov_b32_e32 v163, 0xf149f2ca
	v_mov_b32_e32 v164, 0xf149f2ca
	v_mov_b32_e32 v161, 0xf149f2ca
	v_mov_b32_e32 v162, 0xf149f2ca
	v_mov_b32_e32 v159, 0xf149f2ca
	s_xor_b64 exec, exec, s[22:23]
	s_cbranch_execz .LBB0_258
	ds_read_b32 v144, v193 offset:252
	v_mov_b32_e32 v161, 0xf149f2ca
	v_mov_b32_e32 v162, 0xf149f2ca
	v_mov_b32_e32 v163, 0xf149f2ca
	v_mov_b32_e32 v164, 0xf149f2ca
	v_mov_b32_e32 v165, 0xf149f2ca
	v_mov_b32_e32 v166, 0xf149f2ca
	v_mov_b32_e32 v167, 0xf149f2ca
	v_mov_b32_e32 v205, 0xf149f2ca
	v_mov_b32_e32 v206, 0xf149f2ca
	v_mov_b32_e32 v207, 0xf149f2ca
	v_mov_b32_e32 v208, 0xf149f2ca
	v_mov_b32_e32 v209, 0xf149f2ca
	v_mov_b32_e32 v210, 0xf149f2ca
	v_mov_b32_e32 v211, 0xf149f2ca
	v_mov_b32_e32 v212, 0xf149f2ca
	v_mov_b32_e32 v213, 0xf149f2ca
	ds_read_b32 v162, v193 offset:124
	ds_read_b32 v161, v193 offset:128
	ds_read_b32 v164, v193 offset:132
	ds_read_b32 v163, v193 offset:136
	ds_read_b32 v166, v193 offset:156
	ds_read_b32 v165, v193 offset:160
	ds_read_b32 v205, v193 offset:164
	ds_read_b32 v167, v193 offset:168
	ds_read_b32 v207, v193 offset:188
	ds_read_b32 v206, v193 offset:192
	ds_read_b32 v209, v193 offset:196
	ds_read_b32 v208, v193 offset:200
	ds_read_b32 v211, v193 offset:220
	ds_read_b32 v210, v193 offset:224
	ds_read_b32 v213, v193 offset:228
	ds_read_b32 v212, v193 offset:232
	s_waitcnt lgkmcnt(0)
; __device__ __forceinline__ void partialSM(f32x16& p0, f32x16& p1, float& m_reg, float& mn, float& alpha) {
;     ...
;   float mnC = -mn * C;
;   for (int r = 0; r < 16; ++r) p0[r] = fmaf(p0[r], C, mnC); for (int r = 0; r < 16; ++r) p1[r] = fmaf(p1[r], C, mnC);
;   for (int r = 0; r < 16; ++r) p0[r] = __builtin_amdgcn_exp2f(p0[r]);
; }
; __device__ __forceinline__ void finishSM(f32x16& p0, f32x16& p1, float alpha, float& l_reg, bf16x8& pa0, bf16x8& pa1, bf16x8& pa2, bf16x8& pa3) {
;   for (int r = 0; r < 16; ++r) p1[r] = __builtin_amdgcn_exp2f(p1[r]);
;   float ps = 0; for (int r = 0; r < 16; ++r) ps += p0[r]; for (int r = 0; r < 16; ++r) ps += p1[r];
;   { auto rr = __builtin_amdgcn_permlane32_swap(__float_as_uint(ps), __float_as_uint(ps), false, false);
;     ps = __uint_as_float(rr[0]) + __uint_as_float(rr[1]); }
;   l_reg = l_reg * alpha + ps;
; __device__ __forceinline__ void na_mask(f32x16& p0, f32x16& p1, int kr, int r0, int qrow, int qc, int c0, int hi, const float* bl) {
;     ...
;     const int d = 4 * hi - c0;
; #pragma unroll
;     for (int r = 0; r < 16; ++r) {
;       const int kc = (r & 3) + 8 * (r >> 2);
;       const float b0 = brow[kc], b1 = brow[kc + 32];
;       p0[r] = (unsigned)(d + kc) < 16u ? p0[r] + b0 : -1e30f; p1[r] = (unsigned)(d + kc + 32) < 16u ? p1[r] + b1 : -1e30f;
;     }
;   }
	v_add_f32_e32 v162, v80, v162
	v_add_f32_e32 v161, v81, v161
	v_add_f32_e32 v164, v82, v164
	v_add_f32_e32 v163, v83, v163
	v_add_f32_e32 v166, v84, v166
	v_add_f32_e32 v165, v85, v165
	v_add_f32_e32 v205, v86, v205
	v_add_f32_e32 v167, v87, v167
	v_add_f32_e32 v207, v88, v207
	v_add_f32_e32 v206, v89, v206
	v_add_f32_e32 v209, v90, v209
	v_add_f32_e32 v208, v91, v208
	v_add_f32_e32 v211, v92, v211
	v_add_f32_e32 v210, v93, v210
	v_add_f32_e32 v213, v94, v213
	v_add_f32_e32 v212, v95, v212
	ds_read_b32 v80, v193 offset:256
	ds_read_b32 v81, v193 offset:260
	ds_read_b32 v82, v193 offset:264
	ds_read_b32 v83, v193 offset:284
	ds_read_b32 v84, v193 offset:288
	ds_read_b32 v85, v193 offset:292
	ds_read_b32 v86, v193 offset:296
	ds_read_b32 v87, v193 offset:316
	ds_read_b32 v88, v193 offset:320
	ds_read_b32 v89, v193 offset:324
	ds_read_b32 v90, v193 offset:328
	ds_read_b32 v91, v193 offset:348
	ds_read_b32 v92, v193 offset:352
	ds_read_b32 v93, v193 offset:356
	ds_read_b32 v94, v193 offset:360
	v_cndmask_b32_e64 v162, v239, v162, s[42:43]
	v_cndmask_b32_e64 v161, v239, v161, s[46:47]
	v_cndmask_b32_e64 v164, v239, v164, s[50:51]
	v_cndmask_b32_e64 v163, v239, v163, s[54:55]
	v_cndmask_b32_e64 v166, v239, v166, s[58:59]
	v_cndmask_b32_e64 v165, v239, v165, s[62:63]
	v_cndmask_b32_e64 v205, v239, v205, s[66:67]
	v_cndmask_b32_e64 v167, v239, v167, s[70:71]
	v_cndmask_b32_e64 v207, v239, v207, s[74:75]
	v_cndmask_b32_e64 v206, v239, v206, s[78:79]
	v_cndmask_b32_e64 v209, v239, v209, s[82:83]
	v_cndmask_b32_e64 v208, v239, v208, s[86:87]
	v_cndmask_b32_e64 v211, v239, v211, s[90:91]
	v_cndmask_b32_e64 v210, v239, v210, s[94:95]
	v_cndmask_b32_e64 v213, v239, v213, s[4:5]
	v_cndmask_b32_e64 v212, v239, v212, s[8:9]
	s_waitcnt lgkmcnt(0)
	v_add_f32_e32 v64, v64, v144
	v_cndmask_b32_e64 v144, v239, v64, s[44:45]
	v_add_f32_e32 v64, v65, v80
	v_cndmask_b32_e64 v145, v239, v64, s[48:49]
	v_add_f32_e32 v64, v66, v81
	v_cndmask_b32_e64 v146, v239, v64, s[52:53]
	v_add_f32_e32 v64, v67, v82
	v_cndmask_b32_e64 v147, v239, v64, s[56:57]
	v_add_f32_e32 v64, v68, v83
	v_cndmask_b32_e64 v148, v239, v64, s[60:61]
	v_add_f32_e32 v64, v69, v84
	v_cndmask_b32_e64 v149, v239, v64, s[64:65]
	v_add_f32_e32 v64, v70, v85
	v_cndmask_b32_e64 v150, v239, v64, s[68:69]
	v_add_f32_e32 v64, v71, v86
	v_cndmask_b32_e64 v151, v239, v64, s[72:73]
	v_add_f32_e32 v64, v72, v87
	v_cndmask_b32_e64 v152, v239, v64, s[76:77]
	v_add_f32_e32 v64, v73, v88
	v_cndmask_b32_e64 v153, v239, v64, s[80:81]
	v_add_f32_e32 v64, v74, v89
	v_cndmask_b32_e64 v154, v239, v64, s[84:85]
	v_add_f32_e32 v64, v75, v90
	v_cndmask_b32_e64 v155, v239, v64, s[88:89]
	v_add_f32_e32 v64, v76, v91
	v_cndmask_b32_e64 v156, v239, v64, s[92:93]
	v_add_f32_e32 v64, v77, v92
	v_cndmask_b32_e64 v157, v239, v64, s[96:97]
	v_add_f32_e32 v64, v78, v93
	v_cndmask_b32_e64 v158, v239, v64, s[6:7]
	v_add_f32_e32 v64, v79, v94
	v_cndmask_b32_e64 v159, v239, v64, s[10:11]
.LBB0_258:
	s_or_b64 exec, exec, s[22:23]
	v_cndmask_b32_e64 v64, v214, v192, s[18:19]
	v_mul_f32_e32 v65, 0xbe0293ee, v64
	v_fmamk_f32 v66, v222, 0x3e0293ee, v65
	v_fmamk_f32 v67, v221, 0x3e0293ee, v65
	v_exp_f32_e32 v192, v66
	v_fmamk_f32 v68, v224, 0x3e0293ee, v65
	v_exp_f32_e32 v67, v67
	v_fmamk_f32 v69, v223, 0x3e0293ee, v65
	v_fmamk_f32 v84, v196, 0x3e0293ee, v65
	v_exp_f32_e32 v196, v68
	v_fmamk_f32 v70, v226, 0x3e0293ee, v65
	v_fmamk_f32 v71, v225, 0x3e0293ee, v65
	v_fmamk_f32 v72, v229, 0x3e0293ee, v65
	v_fmamk_f32 v73, v228, 0x3e0293ee, v65
	v_fmamk_f32 v74, v232, 0x3e0293ee, v65
	v_fmamk_f32 v75, v230, 0x3e0293ee, v65
	v_fmamk_f32 v76, v236, 0x3e0293ee, v65
	v_fmamk_f32 v77, v234, 0x3e0293ee, v65
	v_fmamk_f32 v78, v240, 0x3e0293ee, v65
	v_fmamk_f32 v79, v238, 0x3e0293ee, v65
	v_fmamk_f32 v80, v245, 0x3e0293ee, v65
	v_fmamk_f32 v81, v244, 0x3e0293ee, v65
	v_fmamk_f32 v82, v198, 0x3e0293ee, v65
	v_fmamk_f32 v83, v197, 0x3e0293ee, v65
	v_fmamk_f32 v85, v203, 0x3e0293ee, v65
	v_fmamk_f32 v86, v235, 0x3e0293ee, v65
	v_fmamk_f32 v87, v237, 0x3e0293ee, v65
	v_fmamk_f32 v88, v251, 0x3e0293ee, v65
	v_fmamk_f32 v89, v250, 0x3e0293ee, v65
	v_fmamk_f32 v90, v249, 0x3e0293ee, v65
	v_fmamk_f32 v91, v248, 0x3e0293ee, v65
	v_fmamk_f32 v92, v247, 0x3e0293ee, v65
	v_fmamk_f32 v93, v246, 0x3e0293ee, v65
	v_fmamk_f32 v94, v243, 0x3e0293ee, v65
	v_fmamk_f32 v95, v242, 0x3e0293ee, v65
	v_fmamk_f32 v160, v241, 0x3e0293ee, v65
	v_fmac_f32_e32 v65, 0x3e0293ee, v199
	v_exp_f32_e32 v69, v69
	v_exp_f32_e32 v70, v70
	v_exp_f32_e32 v197, v65
	v_add_f32_e32 v65, 0, v192
	v_exp_f32_e32 v71, v71
	v_add_f32_e32 v65, v67, v65
	v_exp_f32_e32 v72, v72
	v_add_f32_e32 v65, v196, v65
	v_exp_f32_e32 v73, v73
	v_add_f32_e32 v65, v69, v65
	v_exp_f32_e32 v74, v74
	v_add_f32_e32 v65, v70, v65
	v_exp_f32_e32 v75, v75
	v_add_f32_e32 v65, v71, v65
	v_exp_f32_e32 v76, v76
	v_add_f32_e32 v65, v72, v65
	v_exp_f32_e32 v77, v77
	v_add_f32_e32 v65, v73, v65
	v_exp_f32_e32 v78, v78
	v_add_f32_e32 v65, v74, v65
	v_exp_f32_e32 v79, v79
	v_add_f32_e32 v65, v75, v65
	v_exp_f32_e32 v80, v80
	v_add_f32_e32 v65, v76, v65
	v_exp_f32_e32 v81, v81
	v_add_f32_e32 v65, v77, v65
	v_exp_f32_e32 v82, v82
	v_add_f32_e32 v65, v78, v65
	v_exp_f32_e32 v83, v83
	v_add_f32_e32 v65, v79, v65
	v_exp_f32_e32 v84, v84
	v_add_f32_e32 v65, v80, v65
	v_exp_f32_e32 v85, v85
	v_add_f32_e32 v65, v81, v65
	v_exp_f32_e32 v86, v86
	v_add_f32_e32 v65, v82, v65
	v_exp_f32_e32 v87, v87
	v_add_f32_e32 v65, v83, v65
	v_exp_f32_e32 v88, v88
	v_add_f32_e32 v65, v84, v65
	v_exp_f32_e32 v89, v89
	v_add_f32_e32 v65, v85, v65
	v_exp_f32_e32 v90, v90
	v_add_f32_e32 v65, v86, v65
	v_exp_f32_e32 v91, v91
	v_add_f32_e32 v65, v87, v65
; __device__ __forceinline__ void partialSM(f32x16& p0, f32x16& p1, float& m_reg, float& mn, float& alpha) {
;   constexpr float C = SCALE * 1.4426950408889634f;
;   float pmax = p0[0]; for (int r = 1; r < 16; ++r) pmax = fmaxf(pmax, p0[r]); for (int r = 0; r < 16; ++r) pmax = fmaxf(pmax, p1[r]);
;   { auto rr = __builtin_amdgcn_permlane32_swap(__float_as_uint(pmax), __float_as_uint(pmax), false, false);
;     pmax = fmaxf(__uint_as_float(rr[0]), __uint_as_float(rr[1])); }
;   if (__builtin_expect(__all(pmax - m_reg <= THR / SCALE), 1)) { mn = m_reg; alpha = 1.f; }
;   else { mn = fmaxf(m_reg, pmax); alpha = __builtin_amdgcn_exp2f((m_reg - mn) * C); m_reg = mn; }
; __device__ __forceinline__ void finishSM(f32x16& p0, f32x16& p1, float alpha, float& l_reg, bf16x8& pa0, bf16x8& pa1, bf16x8& pa2, bf16x8& pa3) {
;   for (int r = 0; r < 16; ++r) p1[r] = __builtin_amdgcn_exp2f(p1[r]);
;   float ps = 0; for (int r = 0; r < 16; ++r) ps += p0[r]; for (int r = 0; r < 16; ++r) ps += p1[r];
;   { auto rr = __builtin_amdgcn_permlane32_swap(__float_as_uint(ps), __float_as_uint(ps), false, false);
;     ps = __uint_as_float(rr[0]) + __uint_as_float(rr[1]); }
;   l_reg = l_reg * alpha + ps;
;     ...
;   PK4(p0, 0, pa0); PK4(p0, 8, pa1); PK4(p1, 0, pa2); PK4(p1, 8, pa3);
; template <int D0> __device__ __forceinline__ void pv_one(f32x16& od, int vb, bf16x8 pa0, bf16x8 pa1, bf16x8 pa2, bf16x8 pa3) {
;   const s16x4 l0 = tr_read<v_rd_off(D0, 0, 0)>(vb), h0 = tr_read<v_rd_off(D0, 0, 1)>(vb), l1 = tr_read<v_rd_off(D0, 1, 0)>(vb), h1 = tr_read<v_rd_off(D0, 1, 1)>(vb);
;   const s16x4 l2 = tr_read<v_rd_off(D0, 2, 0)>(vb), h2 = tr_read<v_rd_off(D0, 2, 1)>(vb), l3 = tr_read<v_rd_off(D0, 3, 0)>(vb), h3 = tr_read<v_rd_off(D0, 3, 1)>(vb);
;   asm volatile("s_waitcnt lgkmcnt(0)" ::: "memory"); SBAR();
;     ...
;   od = __builtin_amdgcn_mfma_f32_32x32x16_bf16(pa0, PK(l0, h0), od, 0, 0, 0);
;   od = __builtin_amdgcn_mfma_f32_32x32x16_bf16(pa1, PK(l1, h1), od, 0, 0, 0);
;   od = __builtin_amdgcn_mfma_f32_32x32x16_bf16(pa2, PK(l2, h2), od, 0, 0, 0);
;   od = __builtin_amdgcn_mfma_f32_32x32x16_bf16(pa3, PK(l3, h3), od, 0, 0, 0);
;     ...
; }
; __device__ __forceinline__ void pv_d0(f32x16* o, int vb, bf16x8 pa0, bf16x8 pa1, bf16x8 pa2, bf16x8 pa3) {
;   pv_one<0>(o[0], vb, pa0, pa1, pa2, pa3); pv_one<1>(o[1], vb, pa0, pa1, pa2, pa3); pv_one<2>(o[2], vb, pa0, pa1, pa2, pa3); pv_one<3>(o[3], vb, pa0, pa1, pa2, pa3);
	v_exp_f32_e32 v92, v92
	v_add_f32_e32 v65, v88, v65
	v_exp_f32_e32 v93, v93
	v_add_f32_e32 v65, v89, v65
	v_exp_f32_e32 v94, v94
	v_add_f32_e32 v65, v90, v65
	v_exp_f32_e32 v95, v95
	v_add_f32_e32 v65, v91, v65
	v_exp_f32_e32 v160, v160
	v_add_f32_e32 v65, v92, v65
	v_add_f32_e32 v65, v93, v65
	v_add_f32_e32 v65, v94, v65
	v_add_f32_e32 v65, v95, v65
	v_add_f32_e32 v65, v160, v65
	v_add_f32_e32 v65, v197, v65
	v_mov_b32_e32 v66, v65
	s_nop 1
	v_permlane32_swap_b32_e32 v65, v66
	v_cvt_pk_bf16_f32 v68, v192, v67
	v_cvt_pk_bf16_f32 v69, v196, v69
	v_cvt_pk_bf16_f32 v70, v70, v71
	v_cvt_pk_bf16_f32 v71, v72, v73
	v_cvt_pk_bf16_f32 v72, v74, v75
	v_cvt_pk_bf16_f32 v73, v76, v77
	v_cvt_pk_bf16_f32 v74, v78, v79
	v_cvt_pk_bf16_f32 v75, v80, v81
	v_cvt_pk_bf16_f32 v76, v82, v83
	v_cvt_pk_bf16_f32 v77, v84, v85
	v_cvt_pk_bf16_f32 v78, v86, v87
	v_cvt_pk_bf16_f32 v79, v88, v89
	v_cvt_pk_bf16_f32 v80, v90, v91
	v_cvt_pk_bf16_f32 v81, v92, v93
	v_cvt_pk_bf16_f32 v82, v94, v95
	v_cvt_pk_bf16_f32 v83, v160, v197
	s_nop 0
	v_permlane32_swap_b32_e32 v68, v70
	v_permlane32_swap_b32_e32 v69, v71
	v_permlane32_swap_b32_e32 v72, v74
	v_permlane32_swap_b32_e32 v73, v75
	v_permlane32_swap_b32_e32 v76, v78
	v_permlane32_swap_b32_e32 v77, v79
	v_permlane32_swap_b32_e32 v80, v82
	v_permlane32_swap_b32_e32 v81, v83
	v_add_u32_e32 v67, s30, v171
	ds_read_b64_tr_b16 v[84:85], v67 offset:0
	ds_read_b64_tr_b16 v[86:87], v67 offset:0x800
	ds_read_b64_tr_b16 v[88:89], v67 offset:0x1000
	ds_read_b64_tr_b16 v[90:91], v67 offset:0x1800
	ds_read_b64_tr_b16 v[92:93], v67 offset:0x2000
	ds_read_b64_tr_b16 v[94:95], v67 offset:0x2800
	ds_read_b64_tr_b16 v[196:197], v67 offset:0x3000
	ds_read_b64_tr_b16 v[198:199], v67 offset:0x3800
	s_waitcnt lgkmcnt(0)
	s_nop 0
	s_setprio 1
	v_mfma_f32_32x32x16_bf16 v[0:15], v[68:71], v[84:87], v[0:15]
	ds_read_b64_tr_b16 v[84:85], v67 offset:0x200
	ds_read_b64_tr_b16 v[86:87], v67 offset:0xa00
	v_mfma_f32_32x32x16_bf16 v[0:15], v[72:75], v[88:91], v[0:15]
	ds_read_b64_tr_b16 v[88:89], v67 offset:0x1200
	ds_read_b64_tr_b16 v[90:91], v67 offset:0x1a00
	v_mfma_f32_32x32x16_bf16 v[0:15], v[76:79], v[92:95], v[0:15]
	ds_read_b64_tr_b16 v[92:93], v67 offset:0x2200
	ds_read_b64_tr_b16 v[94:95], v67 offset:0x2a00
	v_mfma_f32_32x32x16_bf16 v[0:15], v[80:83], v[196:199], v[0:15]
	ds_read_b64_tr_b16 v[196:197], v67 offset:0x3200
	ds_read_b64_tr_b16 v[198:199], v67 offset:0x3a00
	s_waitcnt lgkmcnt(0)
	v_mfma_f32_32x32x16_bf16 v[48:63], v[68:71], v[84:87], v[48:63]
	ds_read_b64_tr_b16 v[84:85], v67 offset:0x400
	ds_read_b64_tr_b16 v[86:87], v67 offset:0xc00
	v_mfma_f32_32x32x16_bf16 v[48:63], v[72:75], v[88:91], v[48:63]
	ds_read_b64_tr_b16 v[88:89], v67 offset:0x1400
	ds_read_b64_tr_b16 v[90:91], v67 offset:0x1c00
	v_mfma_f32_32x32x16_bf16 v[48:63], v[76:79], v[92:95], v[48:63]
	ds_read_b64_tr_b16 v[92:93], v67 offset:0x2400
	ds_read_b64_tr_b16 v[94:95], v67 offset:0x2c00
	v_mfma_f32_32x32x16_bf16 v[48:63], v[80:83], v[196:199], v[48:63]
	ds_read_b64_tr_b16 v[196:197], v67 offset:0x3400
	ds_read_b64_tr_b16 v[198:199], v67 offset:0x3c00
	s_waitcnt lgkmcnt(0)
	v_mfma_f32_32x32x16_bf16 v[32:47], v[68:71], v[84:87], v[32:47]
	ds_read_b64_tr_b16 v[84:85], v67 offset:0x600
	ds_read_b64_tr_b16 v[86:87], v67 offset:0xe00
	v_mfma_f32_32x32x16_bf16 v[32:47], v[72:75], v[88:91], v[32:47]
	ds_read_b64_tr_b16 v[88:89], v67 offset:0x1600
	ds_read_b64_tr_b16 v[90:91], v67 offset:0x1e00
	v_mfma_f32_32x32x16_bf16 v[32:47], v[76:79], v[92:95], v[32:47]
	ds_read_b64_tr_b16 v[92:93], v67 offset:0x2600
	ds_read_b64_tr_b16 v[94:95], v67 offset:0x2e00
	v_mfma_f32_32x32x16_bf16 v[32:47], v[80:83], v[196:199], v[32:47]
	ds_read_b64_tr_b16 v[196:197], v67 offset:0x3600
	ds_read_b64_tr_b16 v[198:199], v67 offset:0x3e00
	s_waitcnt lgkmcnt(0)
	v_mfma_f32_32x32x16_bf16 v[16:31], v[68:71], v[84:87], v[16:31]
	v_max_f32_e32 v67, v161, v161
	v_max_f32_e32 v68, v162, v162
	v_max_f32_e32 v67, v68, v67
	v_max3_f32 v67, v67, v164, v163
	v_max3_f32 v67, v67, v166, v165
	v_max3_f32 v67, v67, v205, v167
	v_max3_f32 v67, v67, v207, v206
	v_max3_f32 v67, v67, v209, v208
	v_max3_f32 v67, v67, v211, v210
	v_mfma_f32_32x32x16_bf16 v[16:31], v[72:75], v[88:91], v[16:31]
	v_max3_f32 v67, v67, v213, v212
	v_max3_f32 v67, v67, v144, v145
	v_max3_f32 v67, v67, v146, v147
	v_max3_f32 v67, v67, v148, v149
	v_max3_f32 v67, v67, v150, v151
	v_max3_f32 v67, v67, v152, v153
	v_max3_f32 v67, v67, v154, v155
	v_max3_f32 v67, v67, v156, v157
	v_mfma_f32_32x32x16_bf16 v[16:31], v[76:79], v[92:95], v[16:31]
	v_max3_f32 v67, v67, v158, v159
	v_mov_b32_e32 v68, v67
	s_nop 1
	v_permlane32_swap_b32_e32 v67, v68
	v_max_f32_e32 v68, v68, v68
	v_max_f32_e32 v67, v67, v67
	v_max_f32_e32 v67, v67, v68
	v_sub_f32_e32 v68, v67, v64
	s_mov_b32 s1, 0x42b504f3
	v_cmp_ge_f32_e32 vcc, s1, v68
	v_max_f32_e32 v68, v64, v64
	v_max_f32_e32 v67, v68, v67
	v_mfma_f32_32x32x16_bf16 v[16:31], v[80:83], v[196:199], v[16:31]
	s_setprio 0
	v_sub_f32_e32 v68, v64, v67
	v_mul_f32_e32 v68, 0x3e0293ee, v68
	v_exp_f32_e32 v68, v68
	s_cmp_eq_u64 vcc, exec
	s_cselect_b64 s[18:19], -1, 0
	v_cndmask_b32_e64 v160, v68, 1.0, s[18:19]
	v_cmp_gt_f32_e32 vcc, 1.0, v160
	s_cbranch_vccz .LBB0_262
	s_and_saveexec_b64 s[14:15], s[12:13]
	ds_write_b32 v181, v160 offset:128
	s_or_b64 exec, exec, s[14:15]
	s_waitcnt lgkmcnt(0)
	v_add_u32_e32 v80, v169, v172
	ds_read_b128 v[68:71], v80 offset:224
	ds_read_b128 v[72:75], v80 offset:192
	ds_read_b128 v[76:79], v80 offset:160
	ds_read_b128 v[80:83], v80 offset:128
	s_waitcnt lgkmcnt(0)
	v_pk_mul_f32 v[12:13], v[12:13], v[68:69]
	v_pk_mul_f32 v[8:9], v[8:9], v[72:73]
	v_pk_mul_f32 v[4:5], v[4:5], v[76:77]
	v_pk_mul_f32 v[14:15], v[14:15], v[70:71]
	v_pk_mul_f32 v[10:11], v[10:11], v[74:75]
	v_pk_mul_f32 v[6:7], v[6:7], v[78:79]
	v_pk_mul_f32 v[2:3], v[2:3], v[82:83]
	v_pk_mul_f32 v[0:1], v[0:1], v[80:81]
	v_pk_mul_f32 v[60:61], v[60:61], v[68:69]
	v_pk_mul_f32 v[56:57], v[56:57], v[72:73]
	v_pk_mul_f32 v[52:53], v[52:53], v[76:77]
	v_pk_mul_f32 v[62:63], v[62:63], v[70:71]
	v_pk_mul_f32 v[58:59], v[58:59], v[74:75]
	v_pk_mul_f32 v[54:55], v[54:55], v[78:79]
	v_pk_mul_f32 v[50:51], v[50:51], v[82:83]
	v_pk_mul_f32 v[48:49], v[48:49], v[80:81]
	v_pk_mul_f32 v[44:45], v[44:45], v[68:69]
	v_pk_mul_f32 v[40:41], v[40:41], v[72:73]
	v_pk_mul_f32 v[36:37], v[36:37], v[76:77]
	v_pk_mul_f32 v[46:47], v[46:47], v[70:71]
	v_pk_mul_f32 v[42:43], v[42:43], v[74:75]
	v_pk_mul_f32 v[38:39], v[38:39], v[78:79]
	v_pk_mul_f32 v[34:35], v[34:35], v[82:83]
	v_pk_mul_f32 v[32:33], v[32:33], v[80:81]
	v_pk_mul_f32 v[28:29], v[28:29], v[68:69]
	v_pk_mul_f32 v[24:25], v[24:25], v[72:73]
	v_pk_mul_f32 v[20:21], v[20:21], v[76:77]
	v_pk_mul_f32 v[30:31], v[30:31], v[70:71]
	v_pk_mul_f32 v[26:27], v[26:27], v[74:75]
	v_pk_mul_f32 v[22:23], v[22:23], v[78:79]
	v_pk_mul_f32 v[18:19], v[18:19], v[82:83]
	v_pk_mul_f32 v[16:17], v[16:17], v[80:81]

; #define SBAR() __builtin_amdgcn_sched_barrier(0)
; #define NAM(P0, P1, t) do { if constexpr (NA) na_mask(P0, P1, kr_lo + (t), r0, qrow, qc, c0, hi, bl); } while (0)
; #define PSM(P0, P1, MN, AL) do { if constexpr (NA) partialSM(P0, P1, m_reg, MN, AL); else { AL = 1.f; _Pragma("unroll") for (int r = 0; r < 16; ++r) P0[r] = __builtin_amdgcn_exp2f(P0[r]); } } while (0)
; #define RESCN(a) do { if constexpr (NA) RESC(a); } while (0)
; #define NAM(P0, P1, t) do { if constexpr (NA) na_mask(P0, P1, kr_lo + (t), r0, qrow, qc, c0, hi, bl); } while (0)
; #define PSM(P0, P1, MN, AL) do { if constexpr (NA) partialSM(P0, P1, m_reg, MN, AL); else { AL = 1.f; _Pragma("unroll") for (int r = 0; r < 16; ++r) P0[r] = __builtin_amdgcn_exp2f(P0[r]); } } while (0)
; template <bool QL>
; __device__ __forceinline__ void qkt(f32x16& p0, f32x16& p1, const bf16* Ks, const bf16x8* qr, const char* ql, int r32, int hi) {
;   p0 = f32x16{}; p1 = f32x16{};
;   for (int d0 = 0; d0 < 8; ++d0) { int cb = (d0 * 16 + hi * 8) * 2;
;     bf16x8 b0 = *reinterpret_cast<const bf16x8*>((const char*)Ks + KSWZ(r32, cb));
;     bf16x8 b1 = *reinterpret_cast<const bf16x8*>((const char*)Ks + KSWZ(32 + r32, cb));
;     bf16x8 q; if constexpr (QL) q = *reinterpret_cast<const bf16x8*>(ql + d0 * 1024); else q = qr[d0];
;     p0 = __builtin_amdgcn_mfma_f32_32x32x16_bf16(b0, q, p0, 0, 0, 0);
;     p1 = __builtin_amdgcn_mfma_f32_32x32x16_bf16(b1, q, p1, 0, 0, 0); }
; }
; __device__ __forceinline__ void na_mask(f32x16& p0, f32x16& p1, int kr, int r0, int qrow, int qc, int c0, int hi, const float* bl) {
;   const bool tv = (kr >= r0) && (kr < r0 + 8);
;   if (!tv) {
; #pragma unroll
;     for (int r = 0; r < 16; ++r) { p0[r] = -1e30f; p1[r] = -1e30f; }
;   } else {
;     const float* brow = bl + (kr - qrow + 7) * 31 + 15 - qc + 4 * hi;
; template <bool NA, int ROWB>
; __device__ __forceinline__ void attn_dma(const bf16* __restrict__ Qb, const bf16* __restrict__ Kh, const bf16* __restrict__ Vh, bf16* __restrict__ Ob, int NT, char* lds, const int tid, float* __restrict__ ssb, int qrow0, int kr_lo, const float* bl) {
;     ...
;   SBAR(); qkt<false>(pB0, pB1, (const bf16*)(K_lds + bc * SHM_K), qr, nullptr, r32, hi); NAM(pB0, pB1, NT - 1);
;   finishSM(pA0, pA1, alA, l_reg, pa0, pa1, pa2, pa3); SBAR();
;   pv_d0(o, vb0 + bp * (int)SHM_V, pa0, pa1, pa2, pa3); PSM(pB0, pB1, mnB, alB); RESCN(alB);
.LBB0_264:
	s_lshl_b32 s0, s0, 14
	s_add_i32 s1, s0, 0
	v_add_u32_e32 v68, s1, v173
	ds_read_b128 v[64:67], v68 offset:49152
	ds_read_b128 v[68:71], v68 offset:57344
	v_add_u32_e32 v161, s1, v174
	s_waitcnt lgkmcnt(1)
	s_setprio 1
	v_mfma_f32_32x32x16_bf16 v[80:95], v[64:67], v[100:103], 0
	s_waitcnt lgkmcnt(0)
	v_mfma_f32_32x32x16_bf16 v[64:79], v[68:71], v[100:103], 0
	ds_read_b128 v[100:103], v161 offset:49152
	ds_read_b128 v[162:165], v161 offset:57344
	s_waitcnt lgkmcnt(1)
	v_mfma_f32_32x32x16_bf16 v[80:95], v[100:103], v[126:129], v[80:95]
	s_waitcnt lgkmcnt(0)
	v_mfma_f32_32x32x16_bf16 v[64:79], v[162:165], v[126:129], v[64:79]
	v_add_u32_e32 v126, s1, v175
	ds_read_b128 v[100:103], v126 offset:49152
	ds_read_b128 v[126:129], v126 offset:57344
	s_waitcnt lgkmcnt(1)
	v_mfma_f32_32x32x16_bf16 v[80:95], v[100:103], v[122:125], v[80:95]
	s_waitcnt lgkmcnt(0)
	v_mfma_f32_32x32x16_bf16 v[64:79], v[126:129], v[122:125], v[64:79]
	v_add_u32_e32 v122, s1, v176
	ds_read_b128 v[100:103], v122 offset:49152
	ds_read_b128 v[122:125], v122 offset:57344
	v_mov_b32_e32 v126, 0xf149f2ca
	v_mov_b32_e32 v127, 0xf149f2ca
	v_mov_b32_e32 v128, 0xf149f2ca
	v_mov_b32_e32 v129, 0xf149f2ca
	s_waitcnt lgkmcnt(1)
	v_mfma_f32_32x32x16_bf16 v[80:95], v[100:103], v[118:121], v[80:95]
	s_waitcnt lgkmcnt(0)
	v_mfma_f32_32x32x16_bf16 v[64:79], v[122:125], v[118:121], v[64:79]
	v_add_u32_e32 v118, s1, v177
	ds_read_b128 v[100:103], v118 offset:49152
	ds_read_b128 v[118:121], v118 offset:57344
	v_mov_b32_e32 v122, 0xf149f2ca
	v_mov_b32_e32 v123, 0xf149f2ca
	v_mov_b32_e32 v124, 0xf149f2ca
	v_mov_b32_e32 v125, 0xf149f2ca
	s_waitcnt lgkmcnt(1)
	v_mfma_f32_32x32x16_bf16 v[80:95], v[100:103], v[114:117], v[80:95]
	s_waitcnt lgkmcnt(0)
	v_mfma_f32_32x32x16_bf16 v[64:79], v[118:121], v[114:117], v[64:79]
	v_add_u32_e32 v114, s1, v178
	ds_read_b128 v[100:103], v114 offset:49152
	ds_read_b128 v[114:117], v114 offset:57344
	v_mov_b32_e32 v118, 0xf149f2ca
	v_mov_b32_e32 v119, 0xf149f2ca
	v_mov_b32_e32 v120, 0xf149f2ca
	v_mov_b32_e32 v121, 0xf149f2ca
	s_waitcnt lgkmcnt(1)
	v_mfma_f32_32x32x16_bf16 v[80:95], v[100:103], v[108:111], v[80:95]
	s_waitcnt lgkmcnt(0)
	v_mfma_f32_32x32x16_bf16 v[64:79], v[114:117], v[108:111], v[64:79]
	v_add_u32_e32 v108, s1, v179
	ds_read_b128 v[100:103], v108 offset:49152
	ds_read_b128 v[108:111], v108 offset:57344
	v_mov_b32_e32 v114, 0xf149f2ca
	v_mov_b32_e32 v117, 0xf149f2ca
	v_mov_b32_e32 v115, 0xf149f2ca
	v_mov_b32_e32 v116, 0xf149f2ca
	s_waitcnt lgkmcnt(1)
	v_mfma_f32_32x32x16_bf16 v[80:95], v[100:103], v[104:107], v[80:95]
	s_waitcnt lgkmcnt(0)
	v_mfma_f32_32x32x16_bf16 v[64:79], v[108:111], v[104:107], v[64:79]
	v_add_u32_e32 v104, s1, v180
	ds_read_b128 v[100:103], v104 offset:49152
	ds_read_b128 v[104:107], v104 offset:57344
	s_add_i32 s1, s37, s16
	s_add_i32 s1, s1, -5
	v_cmp_ge_i32_e32 vcc, s1, v190
	v_cmp_lt_i32_e64 s[18:19], s1, v191
	s_and_b64 s[14:15], vcc, s[18:19]
	s_waitcnt lgkmcnt(1)
	v_mfma_f32_32x32x16_bf16 v[80:95], v[100:103], v[96:99], v[80:95]
	v_mov_b32_e32 v110, 0xf149f2ca
	v_mov_b32_e32 v111, 0xf149f2ca
	v_mov_b32_e32 v108, 0xf149f2ca
	v_mov_b32_e32 v109, 0xf149f2ca
	v_mov_b32_e32 v102, 0xf149f2ca
	v_mov_b32_e32 v103, 0xf149f2ca
	v_mov_b32_e32 v100, 0xf149f2ca
	s_waitcnt lgkmcnt(0)
	v_mfma_f32_32x32x16_bf16 v[64:79], v[104:107], v[96:99], v[64:79]
	s_setprio 0
	v_mov_b32_e32 v106, 0xf149f2ca
	v_mov_b32_e32 v107, 0xf149f2ca
	v_mov_b32_e32 v104, 0xf149f2ca
	v_mov_b32_e32 v105, 0xf149f2ca
	v_mov_b32_e32 v101, 0xf149f2ca
	v_mov_b32_e32 v98, 0xf149f2ca
	v_mov_b32_e32 v99, 0xf149f2ca
	v_mov_b32_e32 v96, 0xf149f2ca
	v_mov_b32_e32 v97, 0xf149f2ca
	s_and_saveexec_b64 s[18:19], s[14:15]
	v_readlane_b32 s27, v254, 25
	s_mov_b32 s30, 0x9000
	s_cbranch_execz .LBB0_298
	v_sub_u32_e32 v96, s1, v189
	s_movk_i32 s1, 0x7c
	v_mul_lo_u32 v96, v96, s1
	v_add_u32_e32 v110, v184, v96
	ds_read_b32 v128, v110 offset:188
	v_mov_b32_e32 v96, 0xf149f2ca
	v_mov_b32_e32 v97, 0xf149f2ca
	v_mov_b32_e32 v98, 0xf149f2ca
	v_mov_b32_e32 v99, 0xf149f2ca
	v_mov_b32_e32 v100, 0xf149f2ca
	v_mov_b32_e32 v101, 0xf149f2ca
	v_mov_b32_e32 v102, 0xf149f2ca
	v_mov_b32_e32 v103, 0xf149f2ca
	v_mov_b32_e32 v104, 0xf149f2ca
	v_mov_b32_e32 v105, 0xf149f2ca
	v_mov_b32_e32 v106, 0xf149f2ca
	v_mov_b32_e32 v107, 0xf149f2ca
	v_mov_b32_e32 v108, 0xf149f2ca
	v_mov_b32_e32 v109, 0xf149f2ca
	v_mov_b32_e32 v115, 0xf149f2ca
	v_mov_b32_e32 v116, 0xf149f2ca
	ds_read_b32 v97, v110 offset:60
	ds_read_b32 v96, v110 offset:64
	ds_read_b32 v99, v110 offset:68
	ds_read_b32 v98, v110 offset:72
	ds_read_b32 v101, v110 offset:92
	ds_read_b32 v100, v110 offset:96
	ds_read_b32 v103, v110 offset:100
	ds_read_b32 v102, v110 offset:104
	ds_read_b32 v105, v110 offset:124
	ds_read_b32 v104, v110 offset:128
	ds_read_b32 v107, v110 offset:132
	ds_read_b32 v106, v110 offset:136
	ds_read_b32 v109, v110 offset:156
	ds_read_b32 v108, v110 offset:160
	ds_read_b32 v116, v110 offset:164
	ds_read_b32 v115, v110 offset:168
	s_waitcnt lgkmcnt(0)
; __device__ __forceinline__ void finishSM(f32x16& p0, f32x16& p1, float alpha, float& l_reg, bf16x8& pa0, bf16x8& pa1, bf16x8& pa2, bf16x8& pa3) {
;   for (int r = 0; r < 16; ++r) p1[r] = __builtin_amdgcn_exp2f(p1[r]);
;   float ps = 0; for (int r = 0; r < 16; ++r) ps += p0[r]; for (int r = 0; r < 16; ++r) ps += p1[r];
;   { auto rr = __builtin_amdgcn_permlane32_swap(__float_as_uint(ps), __float_as_uint(ps), false, false);
;     ps = __uint_as_float(rr[0]) + __uint_as_float(rr[1]); }
;   l_reg = l_reg * alpha + ps;
;     ...
;   PK4(p0, 0, pa0); PK4(p0, 8, pa1); PK4(p1, 0, pa2); PK4(p1, 8, pa3);
; __device__ __forceinline__ void na_mask(f32x16& p0, f32x16& p1, int kr, int r0, int qrow, int qc, int c0, int hi, const float* bl) {
;     ...
;   } else {
;     const float* brow = bl + (kr - qrow + 7) * 31 + 15 - qc + 4 * hi;
;     const int d = 4 * hi - c0;
; #pragma unroll
;     for (int r = 0; r < 16; ++r) {
;       const int kc = (r & 3) + 8 * (r >> 2);
;       const float b0 = brow[kc], b1 = brow[kc + 32];
;       p0[r] = (unsigned)(d + kc) < 16u ? p0[r] + b0 : -1e30f; p1[r] = (unsigned)(d + kc + 32) < 16u ? p1[r] + b1 : -1e30f;
;     }
;   }
	v_add_f32_e32 v97, v80, v97
	v_add_f32_e32 v96, v81, v96
	v_add_f32_e32 v99, v82, v99
	v_add_f32_e32 v98, v83, v98
	v_add_f32_e32 v101, v84, v101
	v_add_f32_e32 v100, v85, v100
	v_add_f32_e32 v103, v86, v103
	v_add_f32_e32 v102, v87, v102
	v_add_f32_e32 v105, v88, v105
	v_add_f32_e32 v104, v89, v104
	v_add_f32_e32 v107, v90, v107
	v_add_f32_e32 v106, v91, v106
	v_add_f32_e32 v109, v92, v109
	v_add_f32_e32 v108, v93, v108
	v_add_f32_e32 v116, v94, v116
	v_add_f32_e32 v115, v95, v115
	ds_read_b32 v80, v110 offset:192
	ds_read_b32 v81, v110 offset:196
	ds_read_b32 v82, v110 offset:200
	ds_read_b32 v83, v110 offset:220
	ds_read_b32 v84, v110 offset:224
	ds_read_b32 v85, v110 offset:228
	ds_read_b32 v86, v110 offset:232
	ds_read_b32 v87, v110 offset:252
	ds_read_b32 v88, v110 offset:256
	ds_read_b32 v89, v110 offset:260
	ds_read_b32 v90, v110 offset:264
	ds_read_b32 v91, v110 offset:284
	ds_read_b32 v92, v110 offset:288
	ds_read_b32 v111, v110 offset:292
	ds_read_b32 v93, v110 offset:296
	v_cndmask_b32_e64 v97, v239, v97, s[42:43]
	v_cndmask_b32_e64 v96, v239, v96, s[46:47]
	v_cndmask_b32_e64 v99, v239, v99, s[50:51]
	v_cndmask_b32_e64 v98, v239, v98, s[54:55]
	v_cndmask_b32_e64 v101, v239, v101, s[58:59]
	v_cndmask_b32_e64 v100, v239, v100, s[62:63]
	v_cndmask_b32_e64 v103, v239, v103, s[66:67]
	v_cndmask_b32_e64 v102, v239, v102, s[70:71]
	v_cndmask_b32_e64 v105, v239, v105, s[74:75]
	v_cndmask_b32_e64 v104, v239, v104, s[78:79]
	v_cndmask_b32_e64 v107, v239, v107, s[82:83]
	v_cndmask_b32_e64 v106, v239, v106, s[86:87]
	v_cndmask_b32_e64 v109, v239, v109, s[90:91]
	v_cndmask_b32_e64 v108, v239, v108, s[94:95]
	v_cndmask_b32_e64 v116, v239, v116, s[4:5]
	v_cndmask_b32_e64 v115, v239, v115, s[8:9]
	s_waitcnt lgkmcnt(14)
	v_add_f32_e32 v64, v64, v128
	s_waitcnt lgkmcnt(1)
	v_add_f32_e32 v78, v78, v111
	v_add_f32_e32 v77, v77, v92
	v_add_f32_e32 v76, v76, v91
	v_add_f32_e32 v75, v75, v90
	v_add_f32_e32 v74, v74, v89
	v_add_f32_e32 v73, v73, v88
	v_add_f32_e32 v72, v72, v87
	v_add_f32_e32 v71, v71, v86
	v_add_f32_e32 v70, v70, v85
	v_add_f32_e32 v69, v69, v84
	v_add_f32_e32 v68, v68, v83
	v_add_f32_e32 v67, v67, v82
	v_add_f32_e32 v66, v66, v81
	v_add_f32_e32 v65, v65, v80
	v_cndmask_b32_e64 v128, v239, v64, s[44:45]
	s_waitcnt lgkmcnt(0)
	v_add_f32_e32 v64, v79, v93
	v_cndmask_b32_e64 v110, v239, v78, s[6:7]
	v_cndmask_b32_e64 v111, v239, v77, s[96:97]
	v_cndmask_b32_e64 v114, v239, v76, s[92:93]
	v_cndmask_b32_e64 v117, v239, v75, s[88:89]
	v_cndmask_b32_e64 v118, v239, v74, s[84:85]
	v_cndmask_b32_e64 v119, v239, v73, s[80:81]
	v_cndmask_b32_e64 v120, v239, v72, s[76:77]
	v_cndmask_b32_e64 v121, v239, v71, s[72:73]
	v_cndmask_b32_e64 v122, v239, v70, s[68:69]
	v_cndmask_b32_e64 v123, v239, v69, s[64:65]
	v_cndmask_b32_e64 v124, v239, v68, s[60:61]
	v_cndmask_b32_e64 v125, v239, v67, s[56:57]
	v_cndmask_b32_e64 v126, v239, v66, s[52:53]
	v_cndmask_b32_e64 v127, v239, v65, s[48:49]
	v_cndmask_b32_e64 v129, v239, v64, s[10:11]
.LBB0_298:
	s_or_b64 exec, exec, s[18:19]
	v_add_f32_e32 v64, 0, v213
	v_add_f32_e32 v64, v217, v64
	v_add_f32_e32 v64, v214, v64
	v_add_f32_e32 v64, v218, v64
	v_add_f32_e32 v64, v215, v64
	v_add_f32_e32 v64, v219, v64
	v_add_f32_e32 v64, v216, v64
	v_add_f32_e32 v64, v220, v64
	v_add_f32_e32 v64, v205, v64
	v_add_f32_e32 v64, v209, v64
	v_add_f32_e32 v64, v206, v64
	v_add_f32_e32 v64, v210, v64
	v_exp_f32_e32 v74, v144
	v_add_f32_e32 v64, v207, v64
	v_exp_f32_e32 v75, v145
	v_add_f32_e32 v64, v211, v64
	v_exp_f32_e32 v76, v146
	v_add_f32_e32 v64, v208, v64
	v_exp_f32_e32 v77, v147
	v_add_f32_e32 v64, v212, v64
	v_exp_f32_e32 v78, v148
	v_add_f32_e32 v64, v74, v64
	v_exp_f32_e32 v79, v149
	v_add_f32_e32 v64, v75, v64
	v_exp_f32_e32 v80, v150
	v_add_f32_e32 v64, v76, v64
	v_exp_f32_e32 v81, v151
	v_add_f32_e32 v64, v77, v64
	v_exp_f32_e32 v82, v152
	v_add_f32_e32 v64, v78, v64
	v_exp_f32_e32 v83, v153
	v_add_f32_e32 v64, v79, v64
	v_exp_f32_e32 v84, v154
	v_add_f32_e32 v64, v80, v64
	v_exp_f32_e32 v85, v155
	v_add_f32_e32 v64, v81, v64
	v_exp_f32_e32 v86, v156
	v_add_f32_e32 v64, v82, v64
	v_exp_f32_e32 v87, v157
	v_add_f32_e32 v64, v83, v64
	v_exp_f32_e32 v88, v158
	v_add_f32_e32 v64, v84, v64
	v_exp_f32_e32 v89, v159
	v_add_f32_e32 v64, v85, v64
	v_add_f32_e32 v64, v86, v64
	v_add_f32_e32 v64, v87, v64
	v_add_f32_e32 v64, v88, v64
	v_add_f32_e32 v64, v89, v64
	v_mov_b32_e32 v65, v64
	v_cvt_pk_bf16_f32 v66, v213, v217
	v_cvt_pk_bf16_f32 v67, v214, v218
	v_cvt_pk_bf16_f32 v68, v215, v219
	v_cvt_pk_bf16_f32 v69, v216, v220
	s_nop 1
	v_permlane32_swap_b32_e32 v64, v65
	v_permlane32_swap_b32_e32 v66, v68
	v_permlane32_swap_b32_e32 v67, v69
	v_cvt_pk_bf16_f32 v70, v205, v209
	v_cvt_pk_bf16_f32 v71, v206, v210
	v_cvt_pk_bf16_f32 v72, v207, v211
	v_cvt_pk_bf16_f32 v73, v208, v212
	v_cvt_pk_bf16_f32 v74, v74, v75
	v_cvt_pk_bf16_f32 v75, v76, v77
	v_cvt_pk_bf16_f32 v76, v78, v79
	v_cvt_pk_bf16_f32 v77, v80, v81
	v_cvt_pk_bf16_f32 v78, v82, v83
	v_cvt_pk_bf16_f32 v79, v84, v85
	v_cvt_pk_bf16_f32 v80, v86, v87
	v_cvt_pk_bf16_f32 v81, v88, v89
	s_nop 0
	v_permlane32_swap_b32_e32 v70, v72
	v_permlane32_swap_b32_e32 v71, v73
	v_permlane32_swap_b32_e32 v74, v76
	v_permlane32_swap_b32_e32 v75, v77
	v_permlane32_swap_b32_e32 v78, v80
	v_permlane32_swap_b32_e32 v79, v81
	v_add_u32_e32 v94, s39, v171
	ds_read_b64_tr_b16 v[82:83], v94 offset:0
	ds_read_b64_tr_b16 v[84:85], v94 offset:0x800
	ds_read_b64_tr_b16 v[86:87], v94 offset:0x1000
	ds_read_b64_tr_b16 v[88:89], v94 offset:0x1800
	ds_read_b64_tr_b16 v[90:91], v94 offset:0x2000
	ds_read_b64_tr_b16 v[92:93], v94 offset:0x2800
	ds_read_b64_tr_b16 v[144:145], v94 offset:0x3000
	ds_read_b64_tr_b16 v[146:147], v94 offset:0x3800
	s_waitcnt lgkmcnt(0)
; #define SBAR() __builtin_amdgcn_sched_barrier(0)
; __device__ __forceinline__ void partialSM(f32x16& p0, f32x16& p1, float& m_reg, float& mn, float& alpha) {
;   constexpr float C = SCALE * 1.4426950408889634f;
;   float pmax = p0[0]; for (int r = 1; r < 16; ++r) pmax = fmaxf(pmax, p0[r]); for (int r = 0; r < 16; ++r) pmax = fmaxf(pmax, p1[r]);
;   { auto rr = __builtin_amdgcn_permlane32_swap(__float_as_uint(pmax), __float_as_uint(pmax), false, false);
;     pmax = fmaxf(__uint_as_float(rr[0]), __uint_as_float(rr[1])); }
;   if (__builtin_expect(__all(pmax - m_reg <= THR / SCALE), 1)) { mn = m_reg; alpha = 1.f; }
;   else { mn = fmaxf(m_reg, pmax); alpha = __builtin_amdgcn_exp2f((m_reg - mn) * C); m_reg = mn; }
;   float mnC = -mn * C;
;   for (int r = 0; r < 16; ++r) p0[r] = fmaf(p0[r], C, mnC); for (int r = 0; r < 16; ++r) p1[r] = fmaf(p1[r], C, mnC);
; template <int D0> __device__ __forceinline__ void pv_one(f32x16& od, int vb, bf16x8 pa0, bf16x8 pa1, bf16x8 pa2, bf16x8 pa3) {
;   const s16x4 l0 = tr_read<v_rd_off(D0, 0, 0)>(vb), h0 = tr_read<v_rd_off(D0, 0, 1)>(vb), l1 = tr_read<v_rd_off(D0, 1, 0)>(vb), h1 = tr_read<v_rd_off(D0, 1, 1)>(vb);
;   const s16x4 l2 = tr_read<v_rd_off(D0, 2, 0)>(vb), h2 = tr_read<v_rd_off(D0, 2, 1)>(vb), l3 = tr_read<v_rd_off(D0, 3, 0)>(vb), h3 = tr_read<v_rd_off(D0, 3, 1)>(vb);
;   asm volatile("s_waitcnt lgkmcnt(0)" ::: "memory"); SBAR();
;     ...
;   od = __builtin_amdgcn_mfma_f32_32x32x16_bf16(pa0, PK(l0, h0), od, 0, 0, 0);
;   od = __builtin_amdgcn_mfma_f32_32x32x16_bf16(pa1, PK(l1, h1), od, 0, 0, 0);
;   od = __builtin_amdgcn_mfma_f32_32x32x16_bf16(pa2, PK(l2, h2), od, 0, 0, 0);
;   od = __builtin_amdgcn_mfma_f32_32x32x16_bf16(pa3, PK(l3, h3), od, 0, 0, 0);
;     ...
; }
; __device__ __forceinline__ void pv_d0(f32x16* o, int vb, bf16x8 pa0, bf16x8 pa1, bf16x8 pa2, bf16x8 pa3) {
;   pv_one<0>(o[0], vb, pa0, pa1, pa2, pa3); pv_one<1>(o[1], vb, pa0, pa1, pa2, pa3); pv_one<2>(o[2], vb, pa0, pa1, pa2, pa3); pv_one<3>(o[3], vb, pa0, pa1, pa2, pa3);
	s_nop 0
	s_setprio 1
	v_mfma_f32_32x32x16_bf16 v[0:15], v[66:69], v[82:85], v[0:15]
	ds_read_b64_tr_b16 v[82:83], v94 offset:0x200
	ds_read_b64_tr_b16 v[84:85], v94 offset:0xa00
	v_mfma_f32_32x32x16_bf16 v[0:15], v[70:73], v[86:89], v[0:15]
	ds_read_b64_tr_b16 v[86:87], v94 offset:0x1200
	ds_read_b64_tr_b16 v[88:89], v94 offset:0x1a00
	v_mfma_f32_32x32x16_bf16 v[0:15], v[74:77], v[90:93], v[0:15]
	ds_read_b64_tr_b16 v[90:91], v94 offset:0x2200
	ds_read_b64_tr_b16 v[92:93], v94 offset:0x2a00
	v_mfma_f32_32x32x16_bf16 v[0:15], v[78:81], v[144:147], v[0:15]
	ds_read_b64_tr_b16 v[144:145], v94 offset:0x3200
	ds_read_b64_tr_b16 v[146:147], v94 offset:0x3a00
	s_waitcnt lgkmcnt(0)
	v_mfma_f32_32x32x16_bf16 v[48:63], v[66:69], v[82:85], v[48:63]
	ds_read_b64_tr_b16 v[82:83], v94 offset:0x400
	ds_read_b64_tr_b16 v[84:85], v94 offset:0xc00
	v_mfma_f32_32x32x16_bf16 v[48:63], v[70:73], v[86:89], v[48:63]
	ds_read_b64_tr_b16 v[86:87], v94 offset:0x1400
	ds_read_b64_tr_b16 v[88:89], v94 offset:0x1c00
	v_mfma_f32_32x32x16_bf16 v[48:63], v[74:77], v[90:93], v[48:63]
	ds_read_b64_tr_b16 v[90:91], v94 offset:0x2400
	ds_read_b64_tr_b16 v[92:93], v94 offset:0x2c00
	v_mfma_f32_32x32x16_bf16 v[48:63], v[78:81], v[144:147], v[48:63]
	ds_read_b64_tr_b16 v[144:145], v94 offset:0x3400
	ds_read_b64_tr_b16 v[146:147], v94 offset:0x3c00
	s_waitcnt lgkmcnt(0)
	v_mfma_f32_32x32x16_bf16 v[32:47], v[66:69], v[82:85], v[32:47]
	ds_read_b64_tr_b16 v[82:83], v94 offset:0x600
	ds_read_b64_tr_b16 v[84:85], v94 offset:0xe00
	v_mfma_f32_32x32x16_bf16 v[32:47], v[70:73], v[86:89], v[32:47]
	ds_read_b64_tr_b16 v[86:87], v94 offset:0x1600
	ds_read_b64_tr_b16 v[88:89], v94 offset:0x1e00
	v_mfma_f32_32x32x16_bf16 v[32:47], v[74:77], v[90:93], v[32:47]
	ds_read_b64_tr_b16 v[90:91], v94 offset:0x2600
	ds_read_b64_tr_b16 v[92:93], v94 offset:0x2e00
	v_mfma_f32_32x32x16_bf16 v[32:47], v[78:81], v[144:147], v[32:47]
	ds_read_b64_tr_b16 v[144:145], v94 offset:0x3600
	ds_read_b64_tr_b16 v[146:147], v94 offset:0x3e00
	s_waitcnt lgkmcnt(0)
	v_mfma_f32_32x32x16_bf16 v[16:31], v[66:69], v[82:85], v[16:31]
	v_max_f32_e32 v66, v96, v96
	v_max_f32_e32 v67, v97, v97
	v_max_f32_e32 v66, v67, v66
	v_max3_f32 v66, v66, v99, v98
	v_max3_f32 v66, v66, v101, v100
	v_max3_f32 v66, v66, v103, v102
	v_max3_f32 v66, v66, v105, v104
	v_max3_f32 v66, v66, v107, v106
	v_max3_f32 v66, v66, v109, v108
	v_mfma_f32_32x32x16_bf16 v[16:31], v[70:73], v[86:89], v[16:31]
	v_max3_f32 v66, v66, v116, v115
	v_max3_f32 v66, v66, v128, v127
	v_max3_f32 v66, v66, v126, v125
	v_max3_f32 v66, v66, v124, v123
	v_max3_f32 v66, v66, v122, v121
	v_max3_f32 v66, v66, v120, v119
	v_max3_f32 v66, v66, v118, v117
	v_max3_f32 v66, v66, v114, v111
	v_mfma_f32_32x32x16_bf16 v[16:31], v[74:77], v[90:93], v[16:31]
	v_max3_f32 v66, v66, v110, v129
	v_mov_b32_e32 v67, v66
	s_nop 1
	v_permlane32_swap_b32_e32 v66, v67
	v_max_f32_e32 v67, v67, v67
	v_max_f32_e32 v66, v66, v66
	v_max_f32_e32 v66, v66, v67
	v_sub_f32_e32 v67, v66, v192
	s_mov_b32 s1, 0x42b504f3
	v_cmp_ge_f32_e32 vcc, s1, v67
	v_max_f32_e32 v67, v192, v192
	v_max_f32_e32 v67, v67, v66
	v_mfma_f32_32x32x16_bf16 v[16:31], v[78:81], v[144:147], v[16:31]
	s_setprio 0
	v_sub_f32_e32 v66, v192, v67
	v_mul_f32_e32 v66, 0x3e0293ee, v66
	v_exp_f32_e32 v66, v66
	s_cmp_eq_u64 vcc, exec
	s_cselect_b64 s[18:19], -1, 0
	v_cndmask_b32_e64 v66, v66, 1.0, s[18:19]
	v_cmp_gt_f32_e32 vcc, 1.0, v66
	s_cbranch_vccz .LBB0_302
	s_and_saveexec_b64 s[14:15], s[12:13]
	s_mov_b32 s39, 0x7e000
	v_readlane_b32 s22, v254, 24
	ds_write_b32 v181, v66 offset:128
	s_or_b64 exec, exec, s[14:15]
	s_waitcnt lgkmcnt(0)
	v_add_u32_e32 v80, v169, v172
	ds_read_b128 v[68:71], v80 offset:224
	ds_read_b128 v[72:75], v80 offset:192
	ds_read_b128 v[76:79], v80 offset:160
	ds_read_b128 v[80:83], v80 offset:128
	s_waitcnt lgkmcnt(3)
	v_pk_mul_f32 v[12:13], v[12:13], v[68:69]
	s_waitcnt lgkmcnt(2)
	v_pk_mul_f32 v[8:9], v[8:9], v[72:73]
	s_waitcnt lgkmcnt(1)
	v_pk_mul_f32 v[4:5], v[4:5], v[76:77]
	v_pk_mul_f32 v[14:15], v[14:15], v[70:71]
	v_pk_mul_f32 v[10:11], v[10:11], v[74:75]
	v_pk_mul_f32 v[6:7], v[6:7], v[78:79]
	s_waitcnt lgkmcnt(0)
	v_pk_mul_f32 v[2:3], v[2:3], v[82:83]
	v_pk_mul_f32 v[0:1], v[0:1], v[80:81]
	v_pk_mul_f32 v[60:61], v[60:61], v[68:69]
	v_pk_mul_f32 v[56:57], v[56:57], v[72:73]
	v_pk_mul_f32 v[52:53], v[52:53], v[76:77]
	v_pk_mul_f32 v[62:63], v[62:63], v[70:71]
	v_pk_mul_f32 v[58:59], v[58:59], v[74:75]
	v_pk_mul_f32 v[54:55], v[54:55], v[78:79]
	v_pk_mul_f32 v[50:51], v[50:51], v[82:83]
	v_pk_mul_f32 v[48:49], v[48:49], v[80:81]
	v_pk_mul_f32 v[44:45], v[44:45], v[68:69]
	v_pk_mul_f32 v[40:41], v[40:41], v[72:73]
	v_pk_mul_f32 v[36:37], v[36:37], v[76:77]
	v_pk_mul_f32 v[46:47], v[46:47], v[70:71]
	v_pk_mul_f32 v[42:43], v[42:43], v[74:75]
	v_pk_mul_f32 v[38:39], v[38:39], v[78:79]
	v_pk_mul_f32 v[34:35], v[34:35], v[82:83]
	v_pk_mul_f32 v[32:33], v[32:33], v[80:81]
	v_pk_mul_f32 v[28:29], v[28:29], v[68:69]
	v_pk_mul_f32 v[24:25], v[24:25], v[72:73]
	v_pk_mul_f32 v[20:21], v[20:21], v[76:77]
	v_pk_mul_f32 v[30:31], v[30:31], v[70:71]
	v_pk_mul_f32 v[26:27], v[26:27], v[74:75]
	v_pk_mul_f32 v[22:23], v[22:23], v[78:79]
	v_pk_mul_f32 v[18:19], v[18:19], v[82:83]
	v_pk_mul_f32 v[16:17], v[16:17], v[80:81]
	s_branch .LBB0_303

; #define SBAR() __builtin_amdgcn_sched_barrier(0)
; __device__ __forceinline__ void finishSM(f32x16& p0, f32x16& p1, float alpha, float& l_reg, bf16x8& pa0, bf16x8& pa1, bf16x8& pa2, bf16x8& pa3) {
;   for (int r = 0; r < 16; ++r) p1[r] = __builtin_amdgcn_exp2f(p1[r]);
;   float ps = 0; for (int r = 0; r < 16; ++r) ps += p0[r]; for (int r = 0; r < 16; ++r) ps += p1[r];
;   { auto rr = __builtin_amdgcn_permlane32_swap(__float_as_uint(ps), __float_as_uint(ps), false, false);
;     ps = __uint_as_float(rr[0]) + __uint_as_float(rr[1]); }
;   l_reg = l_reg * alpha + ps;
;     ...
;   PK4(p0, 0, pa0); PK4(p0, 8, pa1); PK4(p1, 0, pa2); PK4(p1, 8, pa3);
; template <int D0> __device__ __forceinline__ void pv_one(f32x16& od, int vb, bf16x8 pa0, bf16x8 pa1, bf16x8 pa2, bf16x8 pa3) {
;   const s16x4 l0 = tr_read<v_rd_off(D0, 0, 0)>(vb), h0 = tr_read<v_rd_off(D0, 0, 1)>(vb), l1 = tr_read<v_rd_off(D0, 1, 0)>(vb), h1 = tr_read<v_rd_off(D0, 1, 1)>(vb);
;   const s16x4 l2 = tr_read<v_rd_off(D0, 2, 0)>(vb), h2 = tr_read<v_rd_off(D0, 2, 1)>(vb), l3 = tr_read<v_rd_off(D0, 3, 0)>(vb), h3 = tr_read<v_rd_off(D0, 3, 1)>(vb);
;   asm volatile("s_waitcnt lgkmcnt(0)" ::: "memory"); SBAR();
;     ...
;   od = __builtin_amdgcn_mfma_f32_32x32x16_bf16(pa0, PK(l0, h0), od, 0, 0, 0);
;   od = __builtin_amdgcn_mfma_f32_32x32x16_bf16(pa1, PK(l1, h1), od, 0, 0, 0);
;   od = __builtin_amdgcn_mfma_f32_32x32x16_bf16(pa2, PK(l2, h2), od, 0, 0, 0);
;   od = __builtin_amdgcn_mfma_f32_32x32x16_bf16(pa3, PK(l3, h3), od, 0, 0, 0);
;     ...
; }
; __device__ __forceinline__ void pv_d0(f32x16* o, int vb, bf16x8 pa0, bf16x8 pa1, bf16x8 pa2, bf16x8 pa3) {
;   pv_one<0>(o[0], vb, pa0, pa1, pa2, pa3); pv_one<1>(o[1], vb, pa0, pa1, pa2, pa3); pv_one<2>(o[2], vb, pa0, pa1, pa2, pa3); pv_one<3>(o[3], vb, pa0, pa1, pa2, pa3);
.LBB0_303:
	v_cndmask_b32_e64 v67, v67, v192, s[18:19]
	v_mul_f32_e32 v67, 0xbe0293ee, v67
	v_fmamk_f32 v68, v97, 0x3e0293ee, v67
	v_fmamk_f32 v69, v96, 0x3e0293ee, v67
	v_fmamk_f32 v70, v99, 0x3e0293ee, v67
	v_exp_f32_e32 v99, v68
	v_exp_f32_e32 v69, v69
	v_fmamk_f32 v71, v98, 0x3e0293ee, v67
	v_fmamk_f32 v73, v100, 0x3e0293ee, v67
	v_exp_f32_e32 v100, v70
	v_fmamk_f32 v72, v101, 0x3e0293ee, v67
	v_fmamk_f32 v74, v103, 0x3e0293ee, v67
	v_fmamk_f32 v75, v102, 0x3e0293ee, v67
	v_fmamk_f32 v76, v105, 0x3e0293ee, v67
	v_fmamk_f32 v77, v104, 0x3e0293ee, v67
	v_fmamk_f32 v78, v107, 0x3e0293ee, v67
	v_fmamk_f32 v79, v106, 0x3e0293ee, v67
	v_fmamk_f32 v80, v109, 0x3e0293ee, v67
	v_fmamk_f32 v81, v108, 0x3e0293ee, v67
	v_fmamk_f32 v82, v116, 0x3e0293ee, v67
	v_fmamk_f32 v83, v115, 0x3e0293ee, v67
	v_fmamk_f32 v84, v128, 0x3e0293ee, v67
	v_fmamk_f32 v85, v127, 0x3e0293ee, v67
	v_fmamk_f32 v86, v126, 0x3e0293ee, v67
	v_fmamk_f32 v87, v125, 0x3e0293ee, v67
	v_fmamk_f32 v88, v124, 0x3e0293ee, v67
	v_fmamk_f32 v89, v123, 0x3e0293ee, v67
	v_fmamk_f32 v90, v122, 0x3e0293ee, v67
	v_fmamk_f32 v91, v121, 0x3e0293ee, v67
	v_fmamk_f32 v92, v120, 0x3e0293ee, v67
	v_fmamk_f32 v93, v119, 0x3e0293ee, v67
	v_fmamk_f32 v94, v118, 0x3e0293ee, v67
	v_fmamk_f32 v95, v117, 0x3e0293ee, v67
	v_fmamk_f32 v96, v114, 0x3e0293ee, v67
	v_fmamk_f32 v97, v111, 0x3e0293ee, v67
	v_fmamk_f32 v98, v110, 0x3e0293ee, v67
	v_fmac_f32_e32 v67, 0x3e0293ee, v129
	v_exp_f32_e32 v71, v71
	v_exp_f32_e32 v72, v72
	v_exp_f32_e32 v101, v67
	v_add_f32_e32 v67, 0, v99
	v_exp_f32_e32 v73, v73
	v_add_f32_e32 v67, v69, v67
	v_exp_f32_e32 v74, v74
	v_add_f32_e32 v67, v100, v67
	v_exp_f32_e32 v75, v75
	v_add_f32_e32 v67, v71, v67
	v_exp_f32_e32 v76, v76
	v_add_f32_e32 v67, v72, v67
	v_exp_f32_e32 v77, v77
	v_add_f32_e32 v67, v73, v67
	v_exp_f32_e32 v78, v78
	v_add_f32_e32 v67, v74, v67
	v_exp_f32_e32 v79, v79
	v_add_f32_e32 v67, v75, v67
	v_exp_f32_e32 v80, v80
	v_add_f32_e32 v67, v76, v67
	v_exp_f32_e32 v81, v81
	v_add_f32_e32 v67, v77, v67
	v_exp_f32_e32 v82, v82
	v_add_f32_e32 v67, v78, v67
	v_exp_f32_e32 v83, v83
	v_add_f32_e32 v67, v79, v67
	v_exp_f32_e32 v84, v84
	v_add_f32_e32 v67, v80, v67
	v_exp_f32_e32 v85, v85
	v_add_f32_e32 v67, v81, v67
	v_exp_f32_e32 v86, v86
	v_add_f32_e32 v67, v82, v67
	v_exp_f32_e32 v87, v87
	v_add_f32_e32 v67, v83, v67
	v_exp_f32_e32 v88, v88
	v_add_f32_e32 v67, v84, v67
	v_exp_f32_e32 v89, v89
	v_add_f32_e32 v67, v85, v67
	v_exp_f32_e32 v90, v90
	v_add_f32_e32 v67, v86, v67
	v_exp_f32_e32 v91, v91
	v_add_f32_e32 v67, v87, v67
	v_exp_f32_e32 v92, v92
	v_add_f32_e32 v67, v88, v67
	v_exp_f32_e32 v93, v93
	v_add_f32_e32 v67, v89, v67
	v_exp_f32_e32 v94, v94
	v_add_f32_e32 v67, v90, v67
	v_exp_f32_e32 v95, v95
	v_add_f32_e32 v67, v91, v67
	v_exp_f32_e32 v96, v96
	v_add_f32_e32 v67, v92, v67
	v_exp_f32_e32 v97, v97
	v_add_f32_e32 v67, v93, v67
	v_exp_f32_e32 v98, v98
	v_add_f32_e32 v67, v94, v67
	v_add_f32_e32 v67, v95, v67
	v_add_f32_e32 v67, v96, v67
	v_add_f32_e32 v67, v97, v67
	v_add_f32_e32 v67, v98, v67
	v_add_f32_e32 v67, v101, v67
	v_mov_b32_e32 v68, v67
	s_nop 1
	v_permlane32_swap_b32_e32 v67, v68
	v_cvt_pk_bf16_f32 v70, v99, v69
	v_cvt_pk_bf16_f32 v71, v100, v71
	v_cvt_pk_bf16_f32 v72, v72, v73
	v_cvt_pk_bf16_f32 v73, v74, v75
	v_cvt_pk_bf16_f32 v74, v76, v77
	v_cvt_pk_bf16_f32 v75, v78, v79
	v_cvt_pk_bf16_f32 v76, v80, v81
	v_cvt_pk_bf16_f32 v77, v82, v83
	v_cvt_pk_bf16_f32 v78, v84, v85
	v_cvt_pk_bf16_f32 v79, v86, v87
	v_cvt_pk_bf16_f32 v80, v88, v89
	v_cvt_pk_bf16_f32 v81, v90, v91
	v_cvt_pk_bf16_f32 v82, v92, v93
	v_cvt_pk_bf16_f32 v83, v94, v95
	v_cvt_pk_bf16_f32 v84, v96, v97
	v_cvt_pk_bf16_f32 v85, v98, v101
	s_nop 0
	v_permlane32_swap_b32_e32 v70, v72
	v_permlane32_swap_b32_e32 v71, v73
	v_permlane32_swap_b32_e32 v74, v76
	v_permlane32_swap_b32_e32 v75, v77
	v_permlane32_swap_b32_e32 v78, v80
	v_permlane32_swap_b32_e32 v79, v81
	v_permlane32_swap_b32_e32 v82, v84
	v_permlane32_swap_b32_e32 v83, v85
	v_add_u32_e32 v69, s0, v171
	ds_read_b64_tr_b16 v[86:87], v69 offset:0
	ds_read_b64_tr_b16 v[88:89], v69 offset:0x800
	ds_read_b64_tr_b16 v[90:91], v69 offset:0x1000
	ds_read_b64_tr_b16 v[92:93], v69 offset:0x1800
	ds_read_b64_tr_b16 v[94:95], v69 offset:0x2000
	ds_read_b64_tr_b16 v[96:97], v69 offset:0x2800
	ds_read_b64_tr_b16 v[98:99], v69 offset:0x3000
	ds_read_b64_tr_b16 v[100:101], v69 offset:0x3800
	s_waitcnt lgkmcnt(0)
	s_nop 0
	s_setprio 1
	v_mfma_f32_32x32x16_bf16 v[0:15], v[70:73], v[86:89], v[0:15]
	ds_read_b64_tr_b16 v[86:87], v69 offset:0x200
	ds_read_b64_tr_b16 v[88:89], v69 offset:0xa00
	v_mfma_f32_32x32x16_bf16 v[0:15], v[74:77], v[90:93], v[0:15]
	ds_read_b64_tr_b16 v[90:91], v69 offset:0x1200
	ds_read_b64_tr_b16 v[92:93], v69 offset:0x1a00
	v_mfma_f32_32x32x16_bf16 v[0:15], v[78:81], v[94:97], v[0:15]
	ds_read_b64_tr_b16 v[94:95], v69 offset:0x2200
	ds_read_b64_tr_b16 v[96:97], v69 offset:0x2a00
	v_mfma_f32_32x32x16_bf16 v[0:15], v[82:85], v[98:101], v[0:15]
	ds_read_b64_tr_b16 v[98:99], v69 offset:0x3200
	ds_read_b64_tr_b16 v[100:101], v69 offset:0x3a00
	s_waitcnt lgkmcnt(0)
	v_mfma_f32_32x32x16_bf16 v[48:63], v[70:73], v[86:89], v[48:63]
	ds_read_b64_tr_b16 v[86:87], v69 offset:0x400
	ds_read_b64_tr_b16 v[88:89], v69 offset:0xc00
	v_mfma_f32_32x32x16_bf16 v[48:63], v[74:77], v[90:93], v[48:63]
	ds_read_b64_tr_b16 v[90:91], v69 offset:0x1400
	ds_read_b64_tr_b16 v[92:93], v69 offset:0x1c00
	v_mfma_f32_32x32x16_bf16 v[48:63], v[78:81], v[94:97], v[48:63]
	ds_read_b64_tr_b16 v[94:95], v69 offset:0x2400
	ds_read_b64_tr_b16 v[96:97], v69 offset:0x2c00
	v_mfma_f32_32x32x16_bf16 v[48:63], v[82:85], v[98:101], v[48:63]
	ds_read_b64_tr_b16 v[98:99], v69 offset:0x3400
	ds_read_b64_tr_b16 v[100:101], v69 offset:0x3c00
	s_waitcnt lgkmcnt(0)
; __device__ __forceinline__ int crow(int r, int hi) { return (r & 3) + 8 * (r >> 2) + 4 * hi; }
; template <bool NA, int ROWB>
; __device__ __forceinline__ void attn_dma(const bf16* __restrict__ Qb, const bf16* __restrict__ Kh, const bf16* __restrict__ Vh, bf16* __restrict__ Ob, int NT, char* lds, const int tid, float* __restrict__ ssb, int qrow0, int kr_lo, const float* bl) {
;     ...
;   pv_d0(o, vb0 + bc * (int)SHM_V, pa0, pa1, pa2, pa3);
;   if (hi == 0) li_l[r32] = l_reg; asm volatile("s_waitcnt lgkmcnt(0)" ::: "memory");
;   float rli[16];
; #pragma unroll
;   for (int r = 0; r < 16; ++r) rli[r] = __builtin_amdgcn_rcpf(li_l[crow(r, hi)]);
	v_mfma_f32_32x32x16_bf16 v[32:47], v[70:73], v[86:89], v[32:47]
	ds_read_b64_tr_b16 v[86:87], v69 offset:0x600
	ds_read_b64_tr_b16 v[88:89], v69 offset:0xe00
	v_mfma_f32_32x32x16_bf16 v[32:47], v[74:77], v[90:93], v[32:47]
	ds_read_b64_tr_b16 v[90:91], v69 offset:0x1600
	ds_read_b64_tr_b16 v[92:93], v69 offset:0x1e00
	v_mfma_f32_32x32x16_bf16 v[32:47], v[78:81], v[94:97], v[32:47]
	ds_read_b64_tr_b16 v[94:95], v69 offset:0x2600
	ds_read_b64_tr_b16 v[96:97], v69 offset:0x2e00
	v_mfma_f32_32x32x16_bf16 v[32:47], v[82:85], v[98:101], v[32:47]
	ds_read_b64_tr_b16 v[98:99], v69 offset:0x3600
	ds_read_b64_tr_b16 v[100:101], v69 offset:0x3e00
	s_waitcnt lgkmcnt(0)
	v_mfma_f32_32x32x16_bf16 v[16:31], v[70:73], v[86:89], v[16:31]
	v_mfma_f32_32x32x16_bf16 v[16:31], v[74:77], v[90:93], v[16:31]
	v_mfma_f32_32x32x16_bf16 v[16:31], v[78:81], v[94:97], v[16:31]
	v_mfma_f32_32x32x16_bf16 v[16:31], v[82:85], v[98:101], v[16:31]
	s_setprio 0
	s_and_saveexec_b64 s[14:15], s[12:13]
	v_add_f32_e32 v64, v64, v65
	v_fmac_f32_e32 v64, v160, v188
	v_add_f32_e32 v65, v67, v68
	v_fmac_f32_e32 v65, v64, v66
	ds_write_b32 v181, v65
	s_or_b64 exec, exec, s[14:15]
	v_readlane_b32 s16, v254, 51
	v_readlane_b32 s17, v254, 52
	s_waitcnt lgkmcnt(0)
	v_add_u32_e32 v72, v169, v172
	s_lshl_b64 s[0:1], s[16:17], 12
	v_readlane_b32 s14, v254, 41
	ds_read_b128 v[64:67], v72
	ds_read_b128 v[68:71], v72 offset:32
	s_add_u32 s0, s14, s0
	v_readlane_b32 s14, v254, 42
	s_addc_u32 s1, s14, s1
	v_readlane_b32 s14, v254, 53
	s_lshl_b32 s14, s14, 1
	s_add_u32 s0, s0, s14
	s_waitcnt lgkmcnt(1)
	v_rcp_f32_e32 v83, v64
	s_addc_u32 s1, s1, 0
	v_mov_b32_e32 v74, v200
	v_rcp_f32_e32 v86, v65
	v_rcp_f32_e32 v87, v66
	v_rcp_f32_e32 v88, v67
	s_waitcnt lgkmcnt(0)
; __device__ __forceinline__ float xs(float v, int o, int lane) { return __int_as_float(__builtin_amdgcn_ds_bpermute((lane ^ o) << 2, __float_as_int(v))); }
; __device__ __forceinline__ void st16_wt(void* p, u32x4 v) { asm volatile("global_store_dwordx4 %0, %1, off sc0 sc1\n\ts_nop 1" :: "v"(p), "v"(v) : "memory"); }
; template <bool NA, int ROWB>
; __device__ __forceinline__ void attn_dma(const bf16* __restrict__ Qb, const bf16* __restrict__ Kh, const bf16* __restrict__ Vh, bf16* __restrict__ Ob, int NT, char* lds, const int tid, float* __restrict__ ssb, int qrow0, int kr_lo, const float* bl) {
;     ...
;   int tid_e = tid; asm volatile("" : "+v"(tid_e));
;   const int lane_e = tid_e & 63, wid_e = tid_e >> 6, r32_e = lane_e & 31, hi_e = lane_e >> 5;
;   char* sg = lds + 100 * 1024 + wid_e * 4096;
; #pragma unroll
;   for (int half = 0; half < 2; ++half) {
;     char* wb_e = sg + hi_e * 1024 + r32_e * 2 + hi_e * 64;
;     char* wb_o = sg + hi_e * 1024 + r32_e * 2 - hi_e * 64;
; #pragma unroll
;     for (int rr = 0; rr < 8; ++rr) { const int r = half * 8 + rr; const int rc = ((rr & 3) + 8 * (rr >> 2)) * 256;
; #pragma unroll
;       for (int d0 = 0; d0 < 4; ++d0) { const float v = o[d0][r] * rli[r]; *(bf16*)(((d0 & 1) ? wb_o : wb_e) + rc + d0 * 64) = (bf16)(cvtpk(v, v) & 0xffffu); } }
;     asm volatile("s_waitcnt lgkmcnt(0)" ::: "memory");
;     const char* rb_e = sg + (lane_e >> 4) * 256 + (lane_e & 15) * 16;
;     const char* rb_o = sg + (lane_e >> 4) * 256 + (((lane_e & 15) * 16) ^ 64);
;     bf16* gb = Ow + (long)(half * 16 + (lane_e >> 4)) * LDO + (lane_e & 15) * 8;
; #pragma unroll
;     for (int i = 0; i < 4; ++i) { const u32x4 w = *(const u32x4*)(((i & 1) ? rb_o : rb_e) + i * 1024); st16_wt(gb + (long)i * 4 * LDO, w);
;       float q = sumsq8(w); q += xs(q, 1, lane_e); q += xs(q, 2, lane_e); q += xs(q, 4, lane_e); q += xs(q, 8, lane_e);
;       if ((lane_e & 15) == 0) ssb[(size_t)(wid_e * QBLK + half * 16 + (lane_e >> 4) + 4 * i) * 16] = q; }
;     asm volatile("s_waitcnt lgkmcnt(0)" ::: "memory");
;   }
	v_rcp_f32_e32 v89, v68
	v_rcp_f32_e32 v90, v69
	v_rcp_f32_e32 v91, v70
	v_rcp_f32_e32 v92, v71
	ds_read_b128 v[68:71], v72 offset:64
	ds_read_b128 v[64:67], v72 offset:96
	v_lshl_add_u64 v[72:73], s[0:1], 0, v[140:141]
	v_readlane_b32 s0, v254, 20
	v_ashrrev_i32_e32 v79, 6, v74
	v_bfe_u32 v75, v74, 5, 1
	v_lshlrev_b32_e32 v80, 1, v74
	v_and_b32_e32 v94, 15, v74
	v_and_b32_e32 v76, 63, v74
	v_lshl_add_u32 v77, v79, 12, s0
	v_lshlrev_b32_e32 v78, 10, v75
	v_and_b32_e32 v80, 62, v80
	v_lshlrev_b32_e32 v81, 6, v75
	v_bfe_u32 v93, v74, 4, 2
	v_lshlrev_b32_e32 v74, 4, v94
	v_mov_b32_e32 v75, v113
	v_add3_u32 v80, v77, v78, v80
	v_lshl_add_u64 v[84:85], v[72:73], 0, v[74:75]
	v_lshlrev_b32_e32 v72, 2, v76
	v_mul_f32_e32 v0, v0, v83
	v_lshl_add_u32 v82, v93, 8, v77
	v_xor_b32_e32 v78, 4, v72
	v_xor_b32_e32 v77, 8, v72
	v_xor_b32_e32 v76, 16, v72
	v_xor_b32_e32 v75, 32, v72
	v_lshl_or_b32 v72, v79, 5, v93
	v_cvt_pk_bf16_f32 v0, v0, v0
	v_add_u32_e32 v79, v80, v81
	ds_write_b16 v79, v0
	v_mul_f32_e32 v0, v48, v83
	v_cvt_pk_bf16_f32 v0, v0, v0
	v_sub_u32_e32 v48, v80, v81
	ds_write_b16 v48, v0 offset:64
	v_mul_f32_e32 v0, v32, v83
	v_cvt_pk_bf16_f32 v0, v0, v0
	ds_write_b16 v79, v0 offset:128
	v_mul_f32_e32 v0, v16, v83
	v_cvt_pk_bf16_f32 v0, v0, v0
	ds_write_b16 v48, v0 offset:192
	v_mul_f32_e32 v0, v1, v86
	v_cvt_pk_bf16_f32 v0, v0, v0
	ds_write_b16 v79, v0 offset:256
	v_mul_f32_e32 v0, v49, v86
	v_cvt_pk_bf16_f32 v0, v0, v0
	ds_write_b16 v48, v0 offset:320
	v_mul_f32_e32 v0, v33, v86
	v_cvt_pk_bf16_f32 v0, v0, v0
	ds_write_b16 v79, v0 offset:384
	v_mul_f32_e32 v0, v17, v86
	v_cvt_pk_bf16_f32 v0, v0, v0
	ds_write_b16 v48, v0 offset:448
	v_mul_f32_e32 v0, v2, v87
	v_cvt_pk_bf16_f32 v0, v0, v0
	ds_write_b16 v79, v0 offset:512
	v_mul_f32_e32 v0, v50, v87
	v_cvt_pk_bf16_f32 v0, v0, v0
	ds_write_b16 v48, v0 offset:576
	v_mul_f32_e32 v0, v34, v87
	v_cvt_pk_bf16_f32 v0, v0, v0
	ds_write_b16 v79, v0 offset:640
	v_mul_f32_e32 v0, v18, v87
	v_cvt_pk_bf16_f32 v0, v0, v0
	ds_write_b16 v48, v0 offset:704
	v_mul_f32_e32 v0, v3, v88
	v_cvt_pk_bf16_f32 v0, v0, v0
	ds_write_b16 v79, v0 offset:768
	v_mul_f32_e32 v0, v51, v88
	v_cvt_pk_bf16_f32 v0, v0, v0
	ds_write_b16 v48, v0 offset:832
	v_mul_f32_e32 v0, v35, v88
	v_cvt_pk_bf16_f32 v0, v0, v0
	ds_write_b16 v79, v0 offset:896
	v_mul_f32_e32 v0, v19, v88
	v_cvt_pk_bf16_f32 v0, v0, v0
	ds_write_b16 v48, v0 offset:960
	v_mul_f32_e32 v0, v4, v89
	v_cvt_pk_bf16_f32 v0, v0, v0
	ds_write_b16 v79, v0 offset:2048
	v_mul_f32_e32 v0, v52, v89
	v_cvt_pk_bf16_f32 v0, v0, v0
	ds_write_b16 v48, v0 offset:2112
	v_mul_f32_e32 v0, v36, v89
	v_cvt_pk_bf16_f32 v0, v0, v0
	ds_write_b16 v79, v0 offset:2176
	v_mul_f32_e32 v0, v20, v89
	v_cvt_pk_bf16_f32 v0, v0, v0
	ds_write_b16 v48, v0 offset:2240
	v_mul_f32_e32 v0, v5, v90
	v_cvt_pk_bf16_f32 v0, v0, v0
	ds_write_b16 v79, v0 offset:2304
	v_mul_f32_e32 v0, v53, v90
	v_cvt_pk_bf16_f32 v0, v0, v0
	ds_write_b16 v48, v0 offset:2368
	v_mul_f32_e32 v0, v37, v90
	v_cvt_pk_bf16_f32 v0, v0, v0
	ds_write_b16 v79, v0 offset:2432
	v_mul_f32_e32 v0, v21, v90
	v_cvt_pk_bf16_f32 v0, v0, v0
	ds_write_b16 v48, v0 offset:2496
	v_mul_f32_e32 v0, v6, v91
	v_cvt_pk_bf16_f32 v0, v0, v0
	ds_write_b16 v79, v0 offset:2560
	v_mul_f32_e32 v0, v54, v91
	v_cvt_pk_bf16_f32 v0, v0, v0
	ds_write_b16 v48, v0 offset:2624
	v_mul_f32_e32 v0, v38, v91
	v_cvt_pk_bf16_f32 v0, v0, v0
	ds_write_b16 v79, v0 offset:2688
	v_mul_f32_e32 v0, v22, v91
	v_cvt_pk_bf16_f32 v0, v0, v0
	ds_write_b16 v48, v0 offset:2752
	v_mul_f32_e32 v0, v7, v92
	v_cvt_pk_bf16_f32 v0, v0, v0
	ds_write_b16 v79, v0 offset:2816
	v_mul_f32_e32 v0, v55, v92
	v_cvt_pk_bf16_f32 v0, v0, v0
	ds_write_b16 v48, v0 offset:2880
	v_mul_f32_e32 v0, v39, v92
	v_cvt_pk_bf16_f32 v0, v0, v0
	ds_write_b16 v79, v0 offset:2944
	v_mul_f32_e32 v0, v23, v92
	v_cvt_pk_bf16_f32 v0, v0, v0
	ds_write_b16 v48, v0 offset:3008
	s_waitcnt lgkmcnt(0)
	v_add_u32_e32 v2, v82, v74
	ds_read_b128 v[4:7], v2
	v_lshlrev_b32_e32 v0, 12, v93
	v_mov_b32_e32 v1, v113
	v_lshl_add_u64 v[0:1], v[84:85], 0, v[0:1]
	s_waitcnt lgkmcnt(0)
	global_store_dwordx4 v[0:1], v[4:7], off sc0 sc1
	s_nop 1
	v_lshlrev_b32_e32 v3, 16, v4
	v_and_b32_e32 v4, 0xffff0000, v4
	v_mul_f32_e32 v4, v4, v4
	v_fmac_f32_e32 v4, v3, v3
	v_lshlrev_b32_e32 v3, 16, v5
	v_and_b32_e32 v5, 0xffff0000, v5
	v_mul_f32_e32 v5, v5, v5
	v_fmac_f32_e32 v5, v3, v3
	v_add_f32_e32 v3, v4, v5
	v_and_b32_e32 v5, 0xffff0000, v6
	v_lshlrev_b32_e32 v4, 16, v6
	v_mul_f32_e32 v5, v5, v5
	v_fmac_f32_e32 v5, v4, v4
	v_add_f32_e32 v3, v5, v3
	v_and_b32_e32 v5, 0xffff0000, v7
	v_lshlrev_b32_e32 v4, 16, v7
	v_mul_f32_e32 v5, v5, v5
	v_fmac_f32_e32 v5, v4, v4
	v_add_f32_e32 v3, v5, v3
	s_nop 1
	v_mov_b32_dpp v4, v3 quad_perm:[1,0,3,2] row_mask:0xf bank_mask:0xf
	s_lshl_b64 s[14:15], s[16:17], 6
	v_readlane_b32 s16, v254, 58
	s_add_u32 s14, s16, s14
	v_readlane_b32 s16, v254, 59
	s_waitcnt lgkmcnt(0)
	v_add_f32_e32 v3, v3, v4
	s_nop 1
	v_mov_b32_dpp v4, v3 quad_perm:[2,3,0,1] row_mask:0xf bank_mask:0xf
	s_addc_u32 s15, s16, s15
	s_lshl_b32 s16, s36, 2
	s_add_u32 s18, s14, s16
	s_addc_u32 s19, s15, 0
	s_waitcnt lgkmcnt(0)
	v_add_f32_e32 v3, v3, v4
	s_nop 1
	v_mov_b32_dpp v4, v3 row_half_mirror row_mask:0xf bank_mask:0xf
	v_cmp_eq_u32_e32 vcc, 0, v94
	s_waitcnt lgkmcnt(0)
	v_add_f32_e32 v3, v3, v4
	s_nop 1
	v_mov_b32_dpp v4, v3 row_mirror row_mask:0xf bank_mask:0xf
	s_and_saveexec_b64 s[14:15], vcc
	s_cbranch_execz .LBB0_307
	v_ashrrev_i32_e32 v73, 31, v72
	v_lshlrev_b64 v[6:7], 6, v[72:73]
	v_lshl_add_u64 v[6:7], s[18:19], 0, v[6:7]
	s_waitcnt lgkmcnt(0)
	v_add_f32_e32 v3, v3, v4
	global_store_dword v[6:7], v3, off
